# w1_relu2_epilogue_adjacent_squares_as_v_pk_mul
# baseline (speedup 1.0000x reference)
.LBB0_850:
	ds_read_b128 v[144:147], v151
	ds_read_b128 v[156:159], v151 offset:1024
	ds_read_b128 v[160:163], v151 offset:2048
	ds_read_b128 v[164:167], v151 offset:3072
	s_add_u32 s36, s34, 0xfffc0080
	s_addc_u32 s37, s35, -1
	s_cmp_eq_u32 s66, 12
	s_cselect_b32 s39, s27, s37
	s_cselect_b32 s38, s62, s36
	s_cselect_b32 s37, s25, s65
	s_cselect_b32 s36, s63, s64
	v_lshl_add_u64 v[172:173], s[34:35], 0, v[136:137]
	s_add_i32 m0, s42, 0xc000
	ds_read_b128 v[168:171], v152
	ds_read_b128 v[176:179], v152 offset:1024
	ds_read_b128 v[180:183], v152 offset:2048
	ds_read_b128 v[184:187], v152 offset:3072
	ds_read_b128 v[188:191], v152 offset:4096
	ds_read_b128 v[192:195], v152 offset:5120
	ds_read_b128 v[196:199], v152 offset:6144
	ds_read_b128 v[200:203], v152 offset:7168
	global_load_lds_dwordx4 v[172:173], off
	s_add_i32 m0, s42, 0xe000
	v_lshl_add_u64 v[172:173], s[34:35], 0, v[138:139]
	global_load_lds_dwordx4 v[172:173], off
	s_waitcnt lgkmcnt(8)
	s_setprio 1
	s_barrier
	s_waitcnt lgkmcnt(0)
	v_mfma_f32_16x16x32_bf16 v[124:127], v[144:147], v[168:171], v[124:127]
	v_mfma_f32_16x16x32_bf16 v[120:123], v[160:163], v[168:171], v[120:123]
	v_mfma_f32_16x16x32_bf16 v[116:119], v[144:147], v[180:183], v[116:119]
	v_mfma_f32_16x16x32_bf16 v[112:115], v[160:163], v[180:183], v[112:115]
	v_mfma_f32_16x16x32_bf16 v[92:95], v[144:147], v[188:191], v[92:95]
	v_mfma_f32_16x16x32_bf16 v[88:91], v[160:163], v[188:191], v[88:91]
	v_mfma_f32_16x16x32_bf16 v[76:79], v[144:147], v[196:199], v[76:79]
	v_mfma_f32_16x16x32_bf16 v[72:75], v[160:163], v[196:199], v[72:75]
	v_mfma_f32_16x16x32_bf16 v[124:127], v[156:159], v[176:179], v[124:127]
	v_mfma_f32_16x16x32_bf16 v[120:123], v[164:167], v[176:179], v[120:123]
	v_mfma_f32_16x16x32_bf16 v[116:119], v[156:159], v[184:187], v[116:119]
	v_mfma_f32_16x16x32_bf16 v[112:115], v[164:167], v[184:187], v[112:115]
	v_mfma_f32_16x16x32_bf16 v[92:95], v[156:159], v[192:195], v[92:95]
	v_mfma_f32_16x16x32_bf16 v[88:91], v[164:167], v[192:195], v[88:91]
	v_mfma_f32_16x16x32_bf16 v[76:79], v[156:159], v[200:203], v[76:79]
	v_mfma_f32_16x16x32_bf16 v[72:75], v[164:167], v[200:203], v[72:75]
	s_barrier
	s_setprio 0
	s_add_i32 s67, s55, s41
	v_lshl_add_u64 v[172:173], s[36:37], 0, v[130:131]
	s_mov_b32 m0, s67
	ds_read_b128 v[204:207], v153
	ds_read_b128 v[212:215], v153 offset:1024
	ds_read_b128 v[216:219], v153 offset:2048
	ds_read_b128 v[220:223], v153 offset:3072
	global_load_lds_dwordx4 v[172:173], off
	s_add_i32 m0, s67, 0x2000
	v_lshl_add_u64 v[208:209], s[36:37], 0, v[134:135]
	global_load_lds_dwordx4 v[208:209], off
	s_setprio 1
	s_barrier
	s_waitcnt lgkmcnt(0)
	v_mfma_f32_16x16x32_bf16 v[108:111], v[204:207], v[168:171], v[108:111]
	v_mfma_f32_16x16x32_bf16 v[104:107], v[216:219], v[168:171], v[104:107]
	v_mfma_f32_16x16x32_bf16 v[100:103], v[204:207], v[180:183], v[100:103]
	v_mfma_f32_16x16x32_bf16 v[96:99], v[216:219], v[180:183], v[96:99]
	v_mfma_f32_16x16x32_bf16 v[84:87], v[204:207], v[188:191], v[84:87]
	v_mfma_f32_16x16x32_bf16 v[80:83], v[216:219], v[188:191], v[80:83]
	v_mfma_f32_16x16x32_bf16 v[68:71], v[204:207], v[196:199], v[68:71]
	v_mfma_f32_16x16x32_bf16 v[64:67], v[216:219], v[196:199], v[64:67]
	v_mfma_f32_16x16x32_bf16 v[108:111], v[212:215], v[176:179], v[108:111]
	v_mfma_f32_16x16x32_bf16 v[104:107], v[220:223], v[176:179], v[104:107]
	v_mfma_f32_16x16x32_bf16 v[100:103], v[212:215], v[184:187], v[100:103]
	v_mfma_f32_16x16x32_bf16 v[96:99], v[220:223], v[184:187], v[96:99]
	v_mfma_f32_16x16x32_bf16 v[84:87], v[212:215], v[192:195], v[84:87]
	v_mfma_f32_16x16x32_bf16 v[80:83], v[220:223], v[192:195], v[80:83]
	v_mfma_f32_16x16x32_bf16 v[68:71], v[212:215], v[200:203], v[68:71]
	v_mfma_f32_16x16x32_bf16 v[64:67], v[220:223], v[200:203], v[64:67]
	s_barrier
	s_setprio 0
	s_mov_b32 m0, s42
	v_lshl_add_u64 v[224:225], s[38:39], 0, v[128:129]
	ds_read_b128 v[168:171], v152 offset:16384
	ds_read_b128 v[176:179], v152 offset:17408
	ds_read_b128 v[180:183], v152 offset:18432
	ds_read_b128 v[184:187], v152 offset:19456
	ds_read_b128 v[188:191], v152 offset:20480
	ds_read_b128 v[192:195], v152 offset:21504
	ds_read_b128 v[196:199], v152 offset:22528
	ds_read_b128 v[200:203], v152 offset:23552
	global_load_lds_dwordx4 v[224:225], off
	s_mov_b32 m0, s43
	v_lshl_add_u64 v[226:227], s[38:39], 0, v[132:133]
	global_load_lds_dwordx4 v[226:227], off
	s_setprio 1
	s_barrier
	s_waitcnt lgkmcnt(0)
	v_mfma_f32_16x16x32_bf16 v[60:63], v[144:147], v[168:171], v[60:63]
	v_mfma_f32_16x16x32_bf16 v[56:59], v[160:163], v[168:171], v[56:59]
	v_mfma_f32_16x16x32_bf16 v[44:47], v[144:147], v[180:183], v[44:47]
	v_mfma_f32_16x16x32_bf16 v[40:43], v[160:163], v[180:183], v[40:43]
	v_mfma_f32_16x16x32_bf16 v[28:31], v[144:147], v[188:191], v[28:31]
	v_mfma_f32_16x16x32_bf16 v[24:27], v[160:163], v[188:191], v[24:27]
	v_mfma_f32_16x16x32_bf16 v[12:15], v[144:147], v[196:199], v[12:15]
	v_mfma_f32_16x16x32_bf16 v[8:11], v[160:163], v[196:199], v[8:11]
	v_mfma_f32_16x16x32_bf16 v[60:63], v[156:159], v[176:179], v[60:63]
	v_mfma_f32_16x16x32_bf16 v[56:59], v[164:167], v[176:179], v[56:59]
	v_mfma_f32_16x16x32_bf16 v[44:47], v[156:159], v[184:187], v[44:47]
	v_mfma_f32_16x16x32_bf16 v[40:43], v[164:167], v[184:187], v[40:43]
	v_mfma_f32_16x16x32_bf16 v[28:31], v[156:159], v[192:195], v[28:31]
	v_mfma_f32_16x16x32_bf16 v[24:27], v[164:167], v[192:195], v[24:27]
	v_mfma_f32_16x16x32_bf16 v[12:15], v[156:159], v[200:203], v[12:15]
	v_mfma_f32_16x16x32_bf16 v[8:11], v[164:167], v[200:203], v[8:11]
	s_barrier
	s_setprio 0
	s_add_u32 s68, s36, 0x40000
	s_addc_u32 s69, s37, 0
	s_add_i32 s67, s56, s41
	s_mov_b32 m0, s67
	v_lshl_add_u64 v[144:145], s[68:69], 0, v[130:131]
	global_load_lds_dwordx4 v[144:145], off
	s_add_i32 m0, s67, 0x2000
	v_lshl_add_u64 v[144:145], s[68:69], 0, v[134:135]
	global_load_lds_dwordx4 v[144:145], off
	s_waitcnt vmcnt(6)
	s_setprio 1
	s_barrier
	v_mfma_f32_16x16x32_bf16 v[52:55], v[204:207], v[168:171], v[52:55]
	v_mfma_f32_16x16x32_bf16 v[48:51], v[216:219], v[168:171], v[48:51]
	v_mfma_f32_16x16x32_bf16 v[36:39], v[204:207], v[180:183], v[36:39]
	v_mfma_f32_16x16x32_bf16 v[32:35], v[216:219], v[180:183], v[32:35]
	v_mfma_f32_16x16x32_bf16 v[20:23], v[204:207], v[188:191], v[20:23]
	v_mfma_f32_16x16x32_bf16 v[16:19], v[216:219], v[188:191], v[16:19]
	v_mfma_f32_16x16x32_bf16 v[4:7], v[204:207], v[196:199], v[4:7]
	v_mfma_f32_16x16x32_bf16 v[0:3], v[216:219], v[196:199], v[0:3]
	v_mfma_f32_16x16x32_bf16 v[52:55], v[212:215], v[176:179], v[52:55]
	v_mfma_f32_16x16x32_bf16 v[48:51], v[220:223], v[176:179], v[48:51]
	v_mfma_f32_16x16x32_bf16 v[36:39], v[212:215], v[184:187], v[36:39]
	v_mfma_f32_16x16x32_bf16 v[32:35], v[220:223], v[184:187], v[32:35]
	v_mfma_f32_16x16x32_bf16 v[20:23], v[212:215], v[192:195], v[20:23]
	v_mfma_f32_16x16x32_bf16 v[16:19], v[220:223], v[192:195], v[16:19]
	v_mfma_f32_16x16x32_bf16 v[4:7], v[212:215], v[200:203], v[4:7]
	v_mfma_f32_16x16x32_bf16 v[0:3], v[220:223], v[200:203], v[0:3]
	s_barrier
	s_setprio 0
	s_add_i32 s67, 0, 0x18000
	v_add_u32_e32 v155, s67, v149
	ds_read_b128 v[144:147], v155
	ds_read_b128 v[156:159], v155 offset:1024
	ds_read_b128 v[160:163], v155 offset:2048
	ds_read_b128 v[164:167], v155 offset:3072
	s_add_u32 s38, s38, 0x40000
	s_addc_u32 s39, s39, 0
	s_mov_b32 m0, s48
	v_lshl_add_u64 v[204:205], s[38:39], 0, v[128:129]
	ds_read_b128 v[168:171], v152 offset:32768
	ds_read_b128 v[176:179], v152 offset:33792
	ds_read_b128 v[180:183], v152 offset:34816
	ds_read_b128 v[184:187], v152 offset:35840
	ds_read_b128 v[188:191], v152 offset:36864
	ds_read_b128 v[192:195], v152 offset:37888
	ds_read_b128 v[196:199], v152 offset:38912
	ds_read_b128 v[200:203], v152 offset:39936
	global_load_lds_dwordx4 v[204:205], off
	s_mov_b32 m0, s49
	v_lshl_add_u64 v[204:205], s[38:39], 0, v[132:133]
	global_load_lds_dwordx4 v[204:205], off
	s_waitcnt lgkmcnt(8)
	s_setprio 1
	s_barrier
	s_waitcnt lgkmcnt(0)
	v_mfma_f32_16x16x32_bf16 v[124:127], v[144:147], v[168:171], v[124:127]
	v_mfma_f32_16x16x32_bf16 v[120:123], v[160:163], v[168:171], v[120:123]
	v_mfma_f32_16x16x32_bf16 v[116:119], v[144:147], v[180:183], v[116:119]
	v_mfma_f32_16x16x32_bf16 v[112:115], v[160:163], v[180:183], v[112:115]
	v_mfma_f32_16x16x32_bf16 v[92:95], v[144:147], v[188:191], v[92:95]
	v_mfma_f32_16x16x32_bf16 v[88:91], v[160:163], v[188:191], v[88:91]
	v_mfma_f32_16x16x32_bf16 v[76:79], v[144:147], v[196:199], v[76:79]
	v_mfma_f32_16x16x32_bf16 v[72:75], v[160:163], v[196:199], v[72:75]
	v_mfma_f32_16x16x32_bf16 v[124:127], v[156:159], v[176:179], v[124:127]
	v_mfma_f32_16x16x32_bf16 v[120:123], v[164:167], v[176:179], v[120:123]
	v_mfma_f32_16x16x32_bf16 v[116:119], v[156:159], v[184:187], v[116:119]
	v_mfma_f32_16x16x32_bf16 v[112:115], v[164:167], v[184:187], v[112:115]
	v_mfma_f32_16x16x32_bf16 v[92:95], v[156:159], v[192:195], v[92:95]
	v_mfma_f32_16x16x32_bf16 v[88:91], v[164:167], v[192:195], v[88:91]
	v_mfma_f32_16x16x32_bf16 v[76:79], v[156:159], v[200:203], v[76:79]
	v_mfma_f32_16x16x32_bf16 v[72:75], v[164:167], v[200:203], v[72:75]
	s_barrier
	s_setprio 0
	s_add_i32 s38, 0, 0x1c000
	s_add_i32 s39, s67, s41
	v_add_u32_e32 v155, s38, v149
	v_lshl_add_u64 v[172:173], v[172:173], 0, s[8:9]
	s_mov_b32 m0, s39
	ds_read_b128 v[204:207], v155
	ds_read_b128 v[212:215], v155 offset:1024
	ds_read_b128 v[216:219], v155 offset:2048
	ds_read_b128 v[220:223], v155 offset:3072
	global_load_lds_dwordx4 v[172:173], off
	s_add_i32 m0, s39, 0x2000
	v_lshl_add_u64 v[172:173], v[208:209], 0, s[8:9]
	global_load_lds_dwordx4 v[172:173], off
	s_setprio 1
	s_barrier
	s_waitcnt lgkmcnt(0)
	v_mfma_f32_16x16x32_bf16 v[108:111], v[204:207], v[168:171], v[108:111]
	v_mfma_f32_16x16x32_bf16 v[104:107], v[216:219], v[168:171], v[104:107]
	v_mfma_f32_16x16x32_bf16 v[100:103], v[204:207], v[180:183], v[100:103]
	v_mfma_f32_16x16x32_bf16 v[96:99], v[216:219], v[180:183], v[96:99]
	v_mfma_f32_16x16x32_bf16 v[84:87], v[204:207], v[188:191], v[84:87]
	v_mfma_f32_16x16x32_bf16 v[80:83], v[216:219], v[188:191], v[80:83]
	v_mfma_f32_16x16x32_bf16 v[68:71], v[204:207], v[196:199], v[68:71]
	v_mfma_f32_16x16x32_bf16 v[64:67], v[216:219], v[196:199], v[64:67]
	v_mfma_f32_16x16x32_bf16 v[108:111], v[212:215], v[176:179], v[108:111]
	v_mfma_f32_16x16x32_bf16 v[104:107], v[220:223], v[176:179], v[104:107]
	v_mfma_f32_16x16x32_bf16 v[100:103], v[212:215], v[184:187], v[100:103]
	v_mfma_f32_16x16x32_bf16 v[96:99], v[220:223], v[184:187], v[96:99]
	v_mfma_f32_16x16x32_bf16 v[84:87], v[212:215], v[192:195], v[84:87]
	v_mfma_f32_16x16x32_bf16 v[80:83], v[220:223], v[192:195], v[80:83]
	v_mfma_f32_16x16x32_bf16 v[68:71], v[212:215], v[200:203], v[68:71]
	v_mfma_f32_16x16x32_bf16 v[64:67], v[220:223], v[200:203], v[64:67]
	s_barrier
	s_setprio 0
	s_mov_b32 m0, s51
	v_lshl_add_u64 v[172:173], v[224:225], 0, s[8:9]
	ds_read_b128 v[168:171], v152 offset:49152
	ds_read_b128 v[176:179], v152 offset:50176
	ds_read_b128 v[180:183], v152 offset:51200
	ds_read_b128 v[184:187], v152 offset:52224
	ds_read_b128 v[188:191], v152 offset:53248
	ds_read_b128 v[192:195], v152 offset:54272
	ds_read_b128 v[196:199], v152 offset:55296
	ds_read_b128 v[200:203], v152 offset:56320
	global_load_lds_dwordx4 v[172:173], off
	s_mov_b32 m0, s52
	v_lshl_add_u64 v[172:173], v[226:227], 0, s[8:9]
	global_load_lds_dwordx4 v[172:173], off
	s_setprio 1
	s_barrier
	s_waitcnt lgkmcnt(0)
	v_mfma_f32_16x16x32_bf16 v[60:63], v[144:147], v[168:171], v[60:63]
	v_mfma_f32_16x16x32_bf16 v[56:59], v[160:163], v[168:171], v[56:59]
	v_mfma_f32_16x16x32_bf16 v[44:47], v[144:147], v[180:183], v[44:47]
	v_mfma_f32_16x16x32_bf16 v[40:43], v[160:163], v[180:183], v[40:43]
	v_mfma_f32_16x16x32_bf16 v[28:31], v[144:147], v[188:191], v[28:31]
	v_mfma_f32_16x16x32_bf16 v[24:27], v[160:163], v[188:191], v[24:27]
	v_mfma_f32_16x16x32_bf16 v[12:15], v[144:147], v[196:199], v[12:15]
	v_mfma_f32_16x16x32_bf16 v[8:11], v[160:163], v[196:199], v[8:11]
	v_mfma_f32_16x16x32_bf16 v[60:63], v[156:159], v[176:179], v[60:63]
	v_mfma_f32_16x16x32_bf16 v[56:59], v[164:167], v[176:179], v[56:59]
	v_mfma_f32_16x16x32_bf16 v[44:47], v[156:159], v[184:187], v[44:47]
	v_mfma_f32_16x16x32_bf16 v[40:43], v[164:167], v[184:187], v[40:43]
	v_mfma_f32_16x16x32_bf16 v[28:31], v[156:159], v[192:195], v[28:31]
	v_mfma_f32_16x16x32_bf16 v[24:27], v[164:167], v[192:195], v[24:27]
	v_mfma_f32_16x16x32_bf16 v[12:15], v[156:159], v[200:203], v[12:15]
	v_mfma_f32_16x16x32_bf16 v[8:11], v[164:167], v[200:203], v[8:11]
	s_barrier
	s_setprio 0
	s_add_u32 s36, s36, 0x40080
	s_addc_u32 s37, s37, 0
	s_add_i32 s38, s38, s41
	s_mov_b32 m0, s38
	v_lshl_add_u64 v[144:145], s[36:37], 0, v[130:131]
	global_load_lds_dwordx4 v[144:145], off
	s_add_i32 m0, s38, 0x2000
	v_lshl_add_u64 v[144:145], s[36:37], 0, v[134:135]
	global_load_lds_dwordx4 v[144:145], off
	s_waitcnt vmcnt(6)
	s_setprio 1
	s_barrier
	v_mfma_f32_16x16x32_bf16 v[52:55], v[204:207], v[168:171], v[52:55]
	v_mfma_f32_16x16x32_bf16 v[48:51], v[216:219], v[168:171], v[48:51]
	v_mfma_f32_16x16x32_bf16 v[36:39], v[204:207], v[180:183], v[36:39]
	v_mfma_f32_16x16x32_bf16 v[32:35], v[216:219], v[180:183], v[32:35]
	v_mfma_f32_16x16x32_bf16 v[20:23], v[204:207], v[188:191], v[20:23]
	v_mfma_f32_16x16x32_bf16 v[16:19], v[216:219], v[188:191], v[16:19]
	v_mfma_f32_16x16x32_bf16 v[4:7], v[204:207], v[196:199], v[4:7]
	v_mfma_f32_16x16x32_bf16 v[0:3], v[216:219], v[196:199], v[0:3]
	v_mfma_f32_16x16x32_bf16 v[52:55], v[212:215], v[176:179], v[52:55]
	v_mfma_f32_16x16x32_bf16 v[48:51], v[220:223], v[176:179], v[48:51]
	v_mfma_f32_16x16x32_bf16 v[36:39], v[212:215], v[184:187], v[36:39]
	v_mfma_f32_16x16x32_bf16 v[32:35], v[220:223], v[184:187], v[32:35]
	v_mfma_f32_16x16x32_bf16 v[20:23], v[212:215], v[192:195], v[20:23]
	v_mfma_f32_16x16x32_bf16 v[16:19], v[220:223], v[192:195], v[16:19]
	v_mfma_f32_16x16x32_bf16 v[4:7], v[212:215], v[200:203], v[4:7]
	v_mfma_f32_16x16x32_bf16 v[0:3], v[220:223], v[200:203], v[0:3]
	s_barrier
	s_setprio 0
	s_add_i32 s66, s66, 2
	s_add_u32 s34, s34, 0x100
	s_addc_u32 s35, s35, 0
	s_add_u32 s64, s64, 0x100
	s_addc_u32 s65, s65, 0
	s_cmp_gt_u32 s66, 13
	s_cbranch_scc0 .LBB0_850
	v_lshl_add_u32 v146, s0, 8, v148
	v_ashrrev_i32_e32 v147, 31, v146
	v_mov_b32_e32 v155, v242
	v_mov_b32_e32 v162, v243
	v_mov_b32_e32 v163, v244
	v_mov_b32_e32 v164, v245
	v_mov_b32_e32 v165, v246
	v_mov_b32_e32 v166, v247
	v_mov_b32_e32 v167, v248
	v_mov_b32_e32 v168, v249
	v_lshl_or_b32 v144, s1, 8, v150
	v_ashrrev_i32_e32 v145, 31, v144
	v_lshlrev_b64 v[158:159], 13, v[146:147]
	v_lshlrev_b64 v[160:161], 1, v[144:145]
	v_lshl_add_u64 v[144:145], s[92:93], 0, v[158:159]
	v_lshl_add_u64 v[144:145], v[144:145], 0, v[160:161]
	v_or_b32_e32 v156, 16, v146
	v_ashrrev_i32_e32 v157, 31, v156
	v_lshlrev_b64 v[156:157], 13, v[156:157]
	v_lshl_add_u64 v[156:157], s[92:93], 0, v[156:157]
	v_lshl_add_u64 v[156:157], v[156:157], 0, v[160:161]
	s_mov_b64 s[36:37], s[30:31]
	s_mov_b64 s[34:35], s[28:29]
	v_fmamk_f32 v147, v155, 0x3a800000, v154
	v_mul_f32_e32 v158, 0x4b800000, v147
	v_cmp_gt_f32_e32 vcc, s57, v147
	v_fmamk_f32 v155, v162, 0x3a800000, v154
	v_mul_f32_e32 v162, 0x4b800000, v155
	v_cndmask_b32_e32 v147, v147, v158, vcc
	v_rsq_f32_e32 v158, v147
	v_cmp_gt_f32_e64 s[0:1], s57, v155
	v_fmamk_f32 v159, v163, 0x3a800000, v154
	v_fmamk_f32 v163, v164, 0x3a800000, v154
	v_cndmask_b32_e64 v155, v155, v162, s[0:1]
	v_rsq_f32_e32 v155, v155
	v_mul_f32_e32 v162, 0x45800000, v158
	v_cndmask_b32_e32 v158, v158, v162, vcc
	v_pk_mul_f32 v[124:125], v[124:125], v[158:159] op_sel_hi:[1,0]
	v_pk_mul_f32 v[104:105], v[104:105], v[158:159] op_sel_hi:[1,0]
	v_fmamk_f32 v164, v165, 0x3a800000, v154
	v_fmamk_f32 v165, v166, 0x3a800000, v154
	v_fmamk_f32 v166, v167, 0x3a800000, v154
	v_mul_f32_e32 v167, 0x45800000, v155
	v_pk_mul_f32 v[126:127], v[126:127], v[158:159] op_sel_hi:[1,0]
	v_pk_mul_f32 v[122:123], v[122:123], v[158:159] op_sel_hi:[1,0]
	v_pk_mul_f32 v[120:121], v[120:121], v[158:159] op_sel_hi:[1,0]
	v_pk_mul_f32 v[108:109], v[108:109], v[158:159] op_sel_hi:[1,0]
	v_pk_mul_f32 v[106:107], v[106:107], v[158:159] op_sel_hi:[1,0]
	v_max_f32_e32 v124, 0, v124
	v_max_f32_e32 v125, 0, v125
	v_max_f32_e32 v104, 0, v104
	v_cndmask_b32_e64 v162, v155, v167, s[0:1]
	v_pk_mul_f32 v[110:111], v[110:111], v[158:159] op_sel_hi:[1,0]
	v_max_f32_e32 v120, 0, v120
	v_max_f32_e32 v121, 0, v121
	v_max_f32_e32 v126, 0, v126
	v_max_f32_e32 v122, 0, v122
	v_max_f32_e32 v127, 0, v127
	v_max_f32_e32 v123, 0, v123
	v_max_f32_e32 v108, 0, v108
	v_max_f32_e32 v109, 0, v109
	v_max_f32_e32 v105, 0, v105
	v_max_f32_e32 v106, 0, v106
	v_max_f32_e32 v107, 0, v107
	v_pk_mul_f32 v[124:125], v[124:125], v[124:125]
	v_mul_f32_e32 v155, v104, v104
	v_cvt_pk_bf16_f32 v104, v124, v125
	v_fmamk_f32 v147, v168, 0x3a800000, v154
	v_pk_mul_f32 v[112:113], v[112:113], v[162:163] op_sel_hi:[1,0]
	v_max_f32_e32 v110, 0, v110
	v_max_f32_e32 v111, 0, v111
	v_pk_mul_f32 v[120:121], v[120:121], v[120:121]
	v_pk_mul_f32 v[126:127], v[126:127], v[126:127]
	v_pk_mul_f32 v[122:123], v[122:123], v[122:123]
	v_pk_mul_f32 v[108:109], v[108:109], v[108:109]
	v_mul_f32_e32 v158, v105, v105
	v_mul_f32_e32 v167, v106, v106
	v_mul_f32_e32 v168, v107, v107
	v_cvt_pk_bf16_f32 v105, v126, v127
	v_cvt_pk_bf16_f32 v106, v120, v121
	v_cvt_pk_bf16_f32 v107, v122, v123
	global_store_dwordx4 v[144:145], v[104:107], off nt
	v_pk_mul_f32 v[116:117], v[116:117], v[162:163] op_sel_hi:[1,0]
	v_pk_mul_f32 v[110:111], v[110:111], v[110:111]
	v_cvt_pk_bf16_f32 v104, v108, v109
	v_cvt_pk_bf16_f32 v105, v110, v111
	v_cvt_pk_bf16_f32 v106, v155, v158
	v_cvt_pk_bf16_f32 v107, v167, v168
	global_store_dwordx4 v[144:145], v[104:107], off offset:256 nt
	v_pk_mul_f32 v[118:119], v[118:119], v[162:163] op_sel_hi:[1,0]
	v_pk_mul_f32 v[114:115], v[114:115], v[162:163] op_sel_hi:[1,0]
	v_max_f32_e32 v104, 0, v112
	v_mul_f32_e32 v106, v104, v104
	v_max_f32_e32 v104, 0, v117
	v_max_f32_e32 v116, 0, v116
	v_max_f32_e32 v107, 0, v113
	v_mul_f32_e32 v104, v104, v104
	v_pk_mul_f32 v[98:99], v[98:99], v[162:163] op_sel_hi:[1,0]
	v_pk_mul_f32 v[96:97], v[96:97], v[162:163] op_sel_hi:[1,0]
	v_mul_f32_e32 v105, v116, v116
	v_mul_f32_e32 v107, v107, v107
	v_max_f32_e32 v108, 0, v118
	v_max_f32_e32 v109, 0, v114
	v_max_f32_e32 v110, 0, v119
	v_max_f32_e32 v111, 0, v115
	v_cvt_pk_bf16_f32 v104, v105, v104
	v_pk_mul_f32 v[102:103], v[102:103], v[162:163] op_sel_hi:[1,0]
	v_pk_mul_f32 v[100:101], v[100:101], v[162:163] op_sel_hi:[1,0]
	v_max_f32_e32 v96, 0, v96
	v_max_f32_e32 v97, 0, v97
	v_max_f32_e32 v98, 0, v98
	v_pk_mul_f32 v[108:109], v[108:109], v[108:109]
	v_pk_mul_f32 v[110:111], v[110:111], v[110:111]
	v_cvt_pk_bf16_f32 v105, v108, v110
	v_cvt_pk_bf16_f32 v106, v106, v107
	v_cvt_pk_bf16_f32 v107, v109, v111
	global_store_dwordx4 v[156:157], v[104:107], off nt
	v_max_f32_e32 v100, 0, v100
	v_max_f32_e32 v99, 0, v99
	v_mul_f32_e32 v104, v96, v96
	v_max_f32_e32 v96, 0, v101
	v_mul_f32_e32 v101, v97, v97
	v_max_f32_e32 v97, 0, v102
	v_mul_f32_e32 v102, v98, v98
	v_max_f32_e32 v98, 0, v103
	v_pk_mul_f32 v[96:97], v[96:97], v[96:97]
	v_pk_mul_f32 v[98:99], v[98:99], v[98:99]
	v_mul_f32_e32 v100, v100, v100
	v_cvt_pk_bf16_f32 v96, v100, v96
	v_cvt_pk_bf16_f32 v97, v97, v98
	v_cvt_pk_bf16_f32 v98, v104, v101
	v_cvt_pk_bf16_f32 v99, v102, v99
	global_store_dwordx4 v[156:157], v[96:99], off offset:256 nt
	v_cmp_gt_f32_e32 vcc, s57, v159
	s_mov_b64 s[0:1], 0x100000
	v_mul_f32_e32 v98, 0x4b800000, v159
	v_cndmask_b32_e32 v98, v159, v98, vcc
	v_rsq_f32_e32 v98, v98
	v_or_b32_e32 v96, 32, v146
	v_ashrrev_i32_e32 v97, 31, v96
	v_lshlrev_b64 v[96:97], 13, v[96:97]
	v_mul_f32_e32 v99, 0x45800000, v98
	v_cndmask_b32_e32 v98, v98, v99, vcc
	v_pk_mul_f32 v[88:89], v[88:89], v[98:99] op_sel_hi:[1,0]
	v_pk_mul_f32 v[92:93], v[92:93], v[98:99] op_sel_hi:[1,0]
	v_pk_mul_f32 v[90:91], v[90:91], v[98:99] op_sel_hi:[1,0]
	v_max_f32_e32 v88, 0, v88
	v_pk_mul_f32 v[94:95], v[94:95], v[98:99] op_sel_hi:[1,0]
	v_mul_f32_e32 v99, v88, v88
	v_max_f32_e32 v88, 0, v93
	v_max_f32_e32 v89, 0, v89
	v_max_f32_e32 v90, 0, v90
	v_lshl_add_u64 v[96:97], s[92:93], 0, v[96:97]
	v_max_f32_e32 v92, 0, v92
	v_mul_f32_e32 v88, v88, v88
	v_mul_f32_e32 v93, v89, v89
	v_max_f32_e32 v89, 0, v94
	v_mul_f32_e32 v94, v90, v90
	v_max_f32_e32 v90, 0, v95
	v_max_f32_e32 v91, 0, v91
	v_pk_mul_f32 v[82:83], v[82:83], v[98:99] op_sel_hi:[1,0]
	v_pk_mul_f32 v[80:81], v[80:81], v[98:99] op_sel_hi:[1,0]
	v_lshl_add_u64 v[96:97], v[96:97], 0, v[160:161]
	v_mul_f32_e32 v92, v92, v92
	v_mul_f32_e32 v89, v89, v89
	v_pk_mul_f32 v[90:91], v[90:91], v[90:91]
	v_cvt_pk_bf16_f32 v88, v92, v88
	v_pk_mul_f32 v[86:87], v[86:87], v[98:99] op_sel_hi:[1,0]
	v_pk_mul_f32 v[84:85], v[84:85], v[98:99] op_sel_hi:[1,0]
	v_max_f32_e32 v80, 0, v80
	v_max_f32_e32 v81, 0, v81
	v_max_f32_e32 v82, 0, v82
	v_cvt_pk_bf16_f32 v89, v89, v90
	v_cvt_pk_bf16_f32 v90, v99, v93
	v_cvt_pk_bf16_f32 v91, v94, v91
	global_store_dwordx4 v[96:97], v[88:91], off nt
	v_max_f32_e32 v84, 0, v84
	v_max_f32_e32 v83, 0, v83
	v_mul_f32_e32 v88, v80, v80
	v_max_f32_e32 v80, 0, v85
	v_mul_f32_e32 v85, v81, v81
	v_max_f32_e32 v81, 0, v86
	v_mul_f32_e32 v86, v82, v82
	v_max_f32_e32 v82, 0, v87
	v_pk_mul_f32 v[80:81], v[80:81], v[80:81]
	v_pk_mul_f32 v[82:83], v[82:83], v[82:83]
	v_mul_f32_e32 v84, v84, v84
	v_cvt_pk_bf16_f32 v80, v84, v80
	v_cvt_pk_bf16_f32 v81, v81, v82
	v_cvt_pk_bf16_f32 v82, v88, v85
	v_cvt_pk_bf16_f32 v83, v86, v83
	global_store_dwordx4 v[96:97], v[80:83], off offset:256 nt
	v_cmp_gt_f32_e32 vcc, s57, v163
	s_nop 0
	v_mul_f32_e32 v82, 0x4b800000, v163
	v_cndmask_b32_e32 v82, v163, v82, vcc
	v_rsq_f32_e32 v82, v82
	v_or_b32_e32 v80, 48, v146
	v_ashrrev_i32_e32 v81, 31, v80
	v_lshlrev_b64 v[80:81], 13, v[80:81]
	v_mul_f32_e32 v83, 0x45800000, v82
	v_cndmask_b32_e32 v82, v82, v83, vcc
	v_pk_mul_f32 v[72:73], v[72:73], v[82:83] op_sel_hi:[1,0]
	v_pk_mul_f32 v[76:77], v[76:77], v[82:83] op_sel_hi:[1,0]
	v_pk_mul_f32 v[74:75], v[74:75], v[82:83] op_sel_hi:[1,0]
	v_max_f32_e32 v72, 0, v72
	v_pk_mul_f32 v[78:79], v[78:79], v[82:83] op_sel_hi:[1,0]
	v_mul_f32_e32 v83, v72, v72
	v_max_f32_e32 v72, 0, v77
	v_max_f32_e32 v73, 0, v73
	v_max_f32_e32 v74, 0, v74
	v_lshl_add_u64 v[80:81], s[92:93], 0, v[80:81]
	v_max_f32_e32 v76, 0, v76
	v_mul_f32_e32 v72, v72, v72
	v_mul_f32_e32 v77, v73, v73
	v_max_f32_e32 v73, 0, v78
	v_mul_f32_e32 v78, v74, v74
	v_max_f32_e32 v74, 0, v79
	v_max_f32_e32 v75, 0, v75
	v_pk_mul_f32 v[64:65], v[64:65], v[82:83] op_sel_hi:[1,0]
	v_lshl_add_u64 v[80:81], v[80:81], 0, v[160:161]
	v_mul_f32_e32 v76, v76, v76
	v_mul_f32_e32 v73, v73, v73
	v_pk_mul_f32 v[74:75], v[74:75], v[74:75]
	v_cvt_pk_bf16_f32 v72, v76, v72
	v_pk_mul_f32 v[68:69], v[68:69], v[82:83] op_sel_hi:[1,0]
	v_max_f32_e32 v64, 0, v64
	v_cvt_pk_bf16_f32 v73, v73, v74
	v_cvt_pk_bf16_f32 v74, v83, v77
	v_cvt_pk_bf16_f32 v75, v78, v75
	global_store_dwordx4 v[80:81], v[72:75], off nt
	v_max_f32_e32 v68, 0, v68
	v_mul_f32_e32 v68, v68, v68
	v_mul_f32_e32 v72, v64, v64
	v_max_f32_e32 v64, 0, v69
	v_mul_f32_e32 v64, v64, v64
	v_cvt_pk_bf16_f32 v64, v68, v64
	v_mul_f32_e32 v68, 0x4b800000, v164
	v_cmp_gt_f32_e32 vcc, s57, v164
	v_pk_mul_f32 v[66:67], v[66:67], v[82:83] op_sel_hi:[1,0]
	v_pk_mul_f32 v[70:71], v[70:71], v[82:83] op_sel_hi:[1,0]
	v_cndmask_b32_e32 v68, v164, v68, vcc
	v_max_f32_e32 v65, 0, v65
	v_max_f32_e32 v66, 0, v66
	v_rsq_f32_e32 v68, v68
	v_mul_f32_e32 v69, v65, v65
	v_max_f32_e32 v65, 0, v70
	v_mul_f32_e32 v70, v66, v66
	v_max_f32_e32 v66, 0, v71
	v_mul_f32_e32 v65, v65, v65
	v_max_f32_e32 v67, 0, v67
	v_pk_mul_f32 v[66:67], v[66:67], v[66:67]
	v_cvt_pk_bf16_f32 v65, v65, v66
	v_cvt_pk_bf16_f32 v66, v72, v69
	v_cvt_pk_bf16_f32 v67, v70, v67
	global_store_dwordx4 v[80:81], v[64:67], off offset:256 nt
	s_nop 1
	v_mul_f32_e32 v66, 0x45800000, v68
	v_cndmask_b32_e32 v66, v68, v66, vcc
	v_pk_mul_f32 v[56:57], v[56:57], v[66:67] op_sel_hi:[1,0]
	v_pk_mul_f32 v[60:61], v[60:61], v[66:67] op_sel_hi:[1,0]
	v_pk_mul_f32 v[58:59], v[58:59], v[66:67] op_sel_hi:[1,0]
	v_max_f32_e32 v56, 0, v56
	v_pk_mul_f32 v[62:63], v[62:63], v[66:67] op_sel_hi:[1,0]
	v_max_f32_e32 v60, 0, v60
	v_mul_f32_e32 v67, v56, v56
	v_max_f32_e32 v56, 0, v61
	v_max_f32_e32 v57, 0, v57
	v_max_f32_e32 v58, 0, v58
	v_mul_f32_e32 v60, v60, v60
	v_mul_f32_e32 v56, v56, v56
	v_mul_f32_e32 v61, v57, v57
	v_max_f32_e32 v57, 0, v62
	v_mul_f32_e32 v62, v58, v58
	v_max_f32_e32 v58, 0, v63
	v_mul_f32_e32 v57, v57, v57
	v_max_f32_e32 v59, 0, v59
	v_pk_mul_f32 v[58:59], v[58:59], v[58:59]
	v_cvt_pk_bf16_f32 v56, v60, v56
	v_add_co_u32_e32 v60, vcc, s58, v144
	v_pk_mul_f32 v[48:49], v[48:49], v[66:67] op_sel_hi:[1,0]
	v_cvt_pk_bf16_f32 v57, v57, v58
	v_cvt_pk_bf16_f32 v58, v67, v61
	v_addc_co_u32_e32 v61, vcc, 0, v145, vcc
	v_pk_mul_f32 v[52:53], v[52:53], v[66:67] op_sel_hi:[1,0]
	v_max_f32_e32 v48, 0, v48
	v_cvt_pk_bf16_f32 v59, v62, v59
	global_store_dwordx4 v[60:61], v[56:59], off nt
	v_max_f32_e32 v52, 0, v52
	v_mul_f32_e32 v52, v52, v52
	v_mul_f32_e32 v56, v48, v48
	v_max_f32_e32 v48, 0, v53
	v_mul_f32_e32 v48, v48, v48
	v_cvt_pk_bf16_f32 v48, v52, v48
	v_mul_f32_e32 v52, 0x4b800000, v165
	v_cmp_gt_f32_e32 vcc, s57, v165
	v_pk_mul_f32 v[50:51], v[50:51], v[66:67] op_sel_hi:[1,0]
	v_pk_mul_f32 v[54:55], v[54:55], v[66:67] op_sel_hi:[1,0]
	v_cndmask_b32_e32 v52, v165, v52, vcc
	v_max_f32_e32 v49, 0, v49
	v_max_f32_e32 v50, 0, v50
	v_rsq_f32_e32 v52, v52
	v_mul_f32_e32 v53, v49, v49
	v_max_f32_e32 v49, 0, v54
	v_mul_f32_e32 v54, v50, v50
	v_max_f32_e32 v50, 0, v55
	v_mul_f32_e32 v49, v49, v49
	v_max_f32_e32 v51, 0, v51
	v_pk_mul_f32 v[50:51], v[50:51], v[50:51]
	v_lshl_add_u64 v[64:65], v[144:145], 0, s[0:1]
	v_cvt_pk_bf16_f32 v49, v49, v50
	v_cvt_pk_bf16_f32 v50, v56, v53
	v_cvt_pk_bf16_f32 v51, v54, v51
	global_store_dwordx4 v[64:65], v[48:51], off offset:256 nt
	s_mov_b32 s1, s24
	s_mov_b32 s0, s26
	v_mul_f32_e32 v50, 0x45800000, v52
	v_cndmask_b32_e32 v50, v52, v50, vcc
	v_pk_mul_f32 v[40:41], v[40:41], v[50:51] op_sel_hi:[1,0]
	v_pk_mul_f32 v[44:45], v[44:45], v[50:51] op_sel_hi:[1,0]
	v_pk_mul_f32 v[42:43], v[42:43], v[50:51] op_sel_hi:[1,0]
	v_max_f32_e32 v40, 0, v40
	v_pk_mul_f32 v[46:47], v[46:47], v[50:51] op_sel_hi:[1,0]
	v_max_f32_e32 v44, 0, v44
	v_mul_f32_e32 v51, v40, v40
	v_max_f32_e32 v40, 0, v45
	v_max_f32_e32 v41, 0, v41
	v_max_f32_e32 v42, 0, v42
	v_mul_f32_e32 v44, v44, v44
	v_mul_f32_e32 v40, v40, v40
	v_mul_f32_e32 v45, v41, v41
	v_max_f32_e32 v41, 0, v46
	v_mul_f32_e32 v46, v42, v42
	v_max_f32_e32 v42, 0, v47
	v_mul_f32_e32 v41, v41, v41
	v_max_f32_e32 v43, 0, v43
	v_pk_mul_f32 v[42:43], v[42:43], v[42:43]
	v_cvt_pk_bf16_f32 v40, v44, v40
	v_add_co_u32_e32 v44, vcc, s59, v144
	v_pk_mul_f32 v[32:33], v[32:33], v[50:51] op_sel_hi:[1,0]
	v_cvt_pk_bf16_f32 v41, v41, v42
	v_cvt_pk_bf16_f32 v42, v51, v45
	v_addc_co_u32_e32 v45, vcc, 0, v145, vcc
	v_pk_mul_f32 v[36:37], v[36:37], v[50:51] op_sel_hi:[1,0]
	v_max_f32_e32 v32, 0, v32
	v_cvt_pk_bf16_f32 v43, v46, v43
	global_store_dwordx4 v[44:45], v[40:43], off nt
	v_max_f32_e32 v36, 0, v36
	v_mul_f32_e32 v36, v36, v36
	v_mul_f32_e32 v40, v32, v32
	v_max_f32_e32 v32, 0, v37
	v_mul_f32_e32 v32, v32, v32
	v_cvt_pk_bf16_f32 v32, v36, v32
	v_mul_f32_e32 v36, 0x4b800000, v166
	v_cmp_gt_f32_e32 vcc, s57, v166
	v_pk_mul_f32 v[34:35], v[34:35], v[50:51] op_sel_hi:[1,0]
	v_pk_mul_f32 v[38:39], v[38:39], v[50:51] op_sel_hi:[1,0]
	v_cndmask_b32_e32 v36, v166, v36, vcc
	v_max_f32_e32 v33, 0, v33
	v_max_f32_e32 v34, 0, v34
	v_rsq_f32_e32 v36, v36
	v_mul_f32_e32 v37, v33, v33
	v_max_f32_e32 v33, 0, v38
	v_mul_f32_e32 v38, v34, v34
	v_max_f32_e32 v34, 0, v39
	v_mul_f32_e32 v33, v33, v33
	v_max_f32_e32 v35, 0, v35
	v_pk_mul_f32 v[34:35], v[34:35], v[34:35]
	v_lshl_add_u64 v[48:49], v[144:145], 0, s[18:19]
	v_cvt_pk_bf16_f32 v33, v33, v34
	v_cvt_pk_bf16_f32 v34, v40, v37
	v_cvt_pk_bf16_f32 v35, v38, v35
	global_store_dwordx4 v[48:49], v[32:35], off offset:256 nt
	s_nop 1
	v_mul_f32_e32 v34, 0x45800000, v36
	v_cndmask_b32_e32 v34, v36, v34, vcc
	v_pk_mul_f32 v[24:25], v[24:25], v[34:35] op_sel_hi:[1,0]
	v_pk_mul_f32 v[28:29], v[28:29], v[34:35] op_sel_hi:[1,0]
	v_pk_mul_f32 v[26:27], v[26:27], v[34:35] op_sel_hi:[1,0]
	v_max_f32_e32 v24, 0, v24
	v_pk_mul_f32 v[30:31], v[30:31], v[34:35] op_sel_hi:[1,0]
	v_max_f32_e32 v28, 0, v28
	v_mul_f32_e32 v35, v24, v24
	v_max_f32_e32 v24, 0, v29
	v_max_f32_e32 v25, 0, v25
	v_max_f32_e32 v26, 0, v26
	v_mul_f32_e32 v28, v28, v28
	v_mul_f32_e32 v24, v24, v24
	v_mul_f32_e32 v29, v25, v25
	v_max_f32_e32 v25, 0, v30
	v_mul_f32_e32 v30, v26, v26
	v_max_f32_e32 v26, 0, v31
	v_mul_f32_e32 v25, v25, v25
	v_max_f32_e32 v27, 0, v27
	v_pk_mul_f32 v[26:27], v[26:27], v[26:27]
	v_cvt_pk_bf16_f32 v24, v28, v24
	v_add_co_u32_e32 v28, vcc, s60, v144
	v_pk_mul_f32 v[16:17], v[16:17], v[34:35] op_sel_hi:[1,0]
	v_cvt_pk_bf16_f32 v25, v25, v26
	v_cvt_pk_bf16_f32 v26, v35, v29
	v_addc_co_u32_e32 v29, vcc, 0, v145, vcc
	v_pk_mul_f32 v[20:21], v[20:21], v[34:35] op_sel_hi:[1,0]
	v_max_f32_e32 v16, 0, v16
	v_cvt_pk_bf16_f32 v27, v30, v27
	global_store_dwordx4 v[28:29], v[24:27], off nt
	v_max_f32_e32 v20, 0, v20
	v_mul_f32_e32 v20, v20, v20
	v_mul_f32_e32 v24, v16, v16
	v_max_f32_e32 v16, 0, v21
	v_mul_f32_e32 v16, v16, v16
	v_cvt_pk_bf16_f32 v16, v20, v16
	v_mul_f32_e32 v20, 0x4b800000, v147
	v_cmp_gt_f32_e32 vcc, s57, v147
	v_pk_mul_f32 v[18:19], v[18:19], v[34:35] op_sel_hi:[1,0]
	v_pk_mul_f32 v[22:23], v[22:23], v[34:35] op_sel_hi:[1,0]
	v_cndmask_b32_e32 v20, v147, v20, vcc
	v_max_f32_e32 v17, 0, v17
	v_max_f32_e32 v18, 0, v18
	v_rsq_f32_e32 v20, v20
	v_mul_f32_e32 v21, v17, v17
	v_max_f32_e32 v17, 0, v22
	v_mul_f32_e32 v22, v18, v18
	v_max_f32_e32 v18, 0, v23
	v_mul_f32_e32 v17, v17, v17
	v_max_f32_e32 v19, 0, v19
	v_pk_mul_f32 v[18:19], v[18:19], v[18:19]
	v_lshl_add_u64 v[32:33], v[144:145], 0, s[20:21]
	v_cvt_pk_bf16_f32 v17, v17, v18
	v_cvt_pk_bf16_f32 v18, v24, v21
	v_cvt_pk_bf16_f32 v19, v22, v19
	global_store_dwordx4 v[32:33], v[16:19], off offset:256 nt
	s_nop 1
	v_mul_f32_e32 v18, 0x45800000, v20
	v_cndmask_b32_e32 v18, v20, v18, vcc
	v_pk_mul_f32 v[8:9], v[8:9], v[18:19] op_sel_hi:[1,0]
	v_pk_mul_f32 v[12:13], v[12:13], v[18:19] op_sel_hi:[1,0]
	v_pk_mul_f32 v[10:11], v[10:11], v[18:19] op_sel_hi:[1,0]
	v_max_f32_e32 v8, 0, v8
	v_pk_mul_f32 v[14:15], v[14:15], v[18:19] op_sel_hi:[1,0]
	v_max_f32_e32 v12, 0, v12
	v_mul_f32_e32 v19, v8, v8
	v_max_f32_e32 v8, 0, v13
	v_max_f32_e32 v9, 0, v9
	v_max_f32_e32 v10, 0, v10
	v_mul_f32_e32 v12, v12, v12
	v_mul_f32_e32 v8, v8, v8
	v_mul_f32_e32 v13, v9, v9
	v_max_f32_e32 v9, 0, v14
	v_mul_f32_e32 v14, v10, v10
	v_max_f32_e32 v10, 0, v15
	v_mul_f32_e32 v9, v9, v9
	v_max_f32_e32 v11, 0, v11
	v_pk_mul_f32 v[10:11], v[10:11], v[10:11]
	v_cvt_pk_bf16_f32 v8, v12, v8
	v_add_co_u32_e32 v12, vcc, s61, v144
	v_pk_mul_f32 v[2:3], v[2:3], v[18:19] op_sel_hi:[1,0]
	v_pk_mul_f32 v[0:1], v[0:1], v[18:19] op_sel_hi:[1,0]
	v_cvt_pk_bf16_f32 v9, v9, v10
	v_cvt_pk_bf16_f32 v10, v19, v13
	v_addc_co_u32_e32 v13, vcc, 0, v145, vcc
	v_pk_mul_f32 v[6:7], v[6:7], v[18:19] op_sel_hi:[1,0]
	v_pk_mul_f32 v[4:5], v[4:5], v[18:19] op_sel_hi:[1,0]
	v_max_f32_e32 v0, 0, v0
	v_max_f32_e32 v1, 0, v1
	v_max_f32_e32 v2, 0, v2
	v_cvt_pk_bf16_f32 v11, v14, v11
	global_store_dwordx4 v[12:13], v[8:11], off nt
	v_max_f32_e32 v3, 0, v3
	v_lshl_add_u64 v[16:17], v[144:145], 0, s[22:23]
	v_mul_f32_e32 v8, v0, v0
	v_max_f32_e32 v0, 0, v5
	v_mul_f32_e32 v5, v1, v1
	v_max_f32_e32 v1, 0, v6
	v_mul_f32_e32 v6, v2, v2
	v_max_f32_e32 v2, 0, v7
	v_max_f32_e32 v4, 0, v4
	v_pk_mul_f32 v[0:1], v[0:1], v[0:1]
	v_pk_mul_f32 v[2:3], v[2:3], v[2:3]
	s_and_b64 vcc, exec, s[6:7]
	v_mul_f32_e32 v4, v4, v4
	v_cvt_pk_bf16_f32 v0, v4, v0
	v_cvt_pk_bf16_f32 v1, v1, v2
	v_cvt_pk_bf16_f32 v2, v8, v5
	v_cvt_pk_bf16_f32 v3, v6, v3
	global_store_dwordx4 v[16:17], v[0:3], off offset:256 nt
	s_cbranch_vccz .LBB0_843
	s_waitcnt vmcnt(0)
	s_cmpk_gt_u32 s33, 0xff
	s_cbranch_scc1 .LBB0_854
	s_barrier

.LBB0_1218:
	ds_read_b128 v[144:147], v151
	ds_read_b128 v[156:159], v151 offset:1024
	ds_read_b128 v[160:163], v151 offset:2048
	ds_read_b128 v[164:167], v151 offset:3072
	s_add_u32 s30, s28, 0xfffc0080
	s_addc_u32 s31, s29, -1
	s_cmp_eq_u32 s63, 12
	s_cselect_b32 s35, s23, s31
	s_cselect_b32 s34, s59, s30
	s_cselect_b32 s31, s21, s62
	s_cselect_b32 s30, s60, s61
	v_lshl_add_u64 v[172:173], s[28:29], 0, v[136:137]
	s_add_i32 m0, s40, 0xc000
	ds_read_b128 v[168:171], v152
	ds_read_b128 v[176:179], v152 offset:1024
	ds_read_b128 v[180:183], v152 offset:2048
	ds_read_b128 v[184:187], v152 offset:3072
	ds_read_b128 v[188:191], v152 offset:4096
	ds_read_b128 v[192:195], v152 offset:5120
	ds_read_b128 v[196:199], v152 offset:6144
	ds_read_b128 v[200:203], v152 offset:7168
	global_load_lds_dwordx4 v[172:173], off
	s_add_i32 m0, s40, 0xe000
	v_lshl_add_u64 v[172:173], s[28:29], 0, v[138:139]
	global_load_lds_dwordx4 v[172:173], off
	s_waitcnt lgkmcnt(8)
	s_setprio 1
	s_barrier
	s_waitcnt lgkmcnt(0)
	v_mfma_f32_16x16x32_bf16 v[124:127], v[144:147], v[168:171], v[124:127]
	v_mfma_f32_16x16x32_bf16 v[120:123], v[160:163], v[168:171], v[120:123]
	v_mfma_f32_16x16x32_bf16 v[116:119], v[144:147], v[180:183], v[116:119]
	v_mfma_f32_16x16x32_bf16 v[112:115], v[160:163], v[180:183], v[112:115]
	v_mfma_f32_16x16x32_bf16 v[92:95], v[144:147], v[188:191], v[92:95]
	v_mfma_f32_16x16x32_bf16 v[88:91], v[160:163], v[188:191], v[88:91]
	v_mfma_f32_16x16x32_bf16 v[76:79], v[144:147], v[196:199], v[76:79]
	v_mfma_f32_16x16x32_bf16 v[72:75], v[160:163], v[196:199], v[72:75]
	v_mfma_f32_16x16x32_bf16 v[124:127], v[156:159], v[176:179], v[124:127]
	v_mfma_f32_16x16x32_bf16 v[120:123], v[164:167], v[176:179], v[120:123]
	v_mfma_f32_16x16x32_bf16 v[116:119], v[156:159], v[184:187], v[116:119]
	v_mfma_f32_16x16x32_bf16 v[112:115], v[164:167], v[184:187], v[112:115]
	v_mfma_f32_16x16x32_bf16 v[92:95], v[156:159], v[192:195], v[92:95]
	v_mfma_f32_16x16x32_bf16 v[88:91], v[164:167], v[192:195], v[88:91]
	v_mfma_f32_16x16x32_bf16 v[76:79], v[156:159], v[200:203], v[76:79]
	v_mfma_f32_16x16x32_bf16 v[72:75], v[164:167], v[200:203], v[72:75]
	s_barrier
	s_setprio 0
	s_add_i32 s64, s52, s39
	v_lshl_add_u64 v[172:173], s[30:31], 0, v[130:131]
	s_mov_b32 m0, s64
	ds_read_b128 v[204:207], v153
	ds_read_b128 v[212:215], v153 offset:1024
	ds_read_b128 v[216:219], v153 offset:2048
	ds_read_b128 v[220:223], v153 offset:3072
	global_load_lds_dwordx4 v[172:173], off
	s_add_i32 m0, s64, 0x2000
	v_lshl_add_u64 v[208:209], s[30:31], 0, v[134:135]
	global_load_lds_dwordx4 v[208:209], off
	s_setprio 1
	s_barrier
	s_waitcnt lgkmcnt(0)
	v_mfma_f32_16x16x32_bf16 v[108:111], v[204:207], v[168:171], v[108:111]
	v_mfma_f32_16x16x32_bf16 v[104:107], v[216:219], v[168:171], v[104:107]
	v_mfma_f32_16x16x32_bf16 v[100:103], v[204:207], v[180:183], v[100:103]
	v_mfma_f32_16x16x32_bf16 v[96:99], v[216:219], v[180:183], v[96:99]
	v_mfma_f32_16x16x32_bf16 v[84:87], v[204:207], v[188:191], v[84:87]
	v_mfma_f32_16x16x32_bf16 v[80:83], v[216:219], v[188:191], v[80:83]
	v_mfma_f32_16x16x32_bf16 v[68:71], v[204:207], v[196:199], v[68:71]
	v_mfma_f32_16x16x32_bf16 v[64:67], v[216:219], v[196:199], v[64:67]
	v_mfma_f32_16x16x32_bf16 v[108:111], v[212:215], v[176:179], v[108:111]
	v_mfma_f32_16x16x32_bf16 v[104:107], v[220:223], v[176:179], v[104:107]
	v_mfma_f32_16x16x32_bf16 v[100:103], v[212:215], v[184:187], v[100:103]
	v_mfma_f32_16x16x32_bf16 v[96:99], v[220:223], v[184:187], v[96:99]
	v_mfma_f32_16x16x32_bf16 v[84:87], v[212:215], v[192:195], v[84:87]
	v_mfma_f32_16x16x32_bf16 v[80:83], v[220:223], v[192:195], v[80:83]
	v_mfma_f32_16x16x32_bf16 v[68:71], v[212:215], v[200:203], v[68:71]
	v_mfma_f32_16x16x32_bf16 v[64:67], v[220:223], v[200:203], v[64:67]
	s_barrier
	s_setprio 0
	s_mov_b32 m0, s40
	v_lshl_add_u64 v[224:225], s[34:35], 0, v[128:129]
	ds_read_b128 v[168:171], v152 offset:16384
	ds_read_b128 v[176:179], v152 offset:17408
	ds_read_b128 v[180:183], v152 offset:18432
	ds_read_b128 v[184:187], v152 offset:19456
	ds_read_b128 v[188:191], v152 offset:20480
	ds_read_b128 v[192:195], v152 offset:21504
	ds_read_b128 v[196:199], v152 offset:22528
	ds_read_b128 v[200:203], v152 offset:23552
	global_load_lds_dwordx4 v[224:225], off
	s_mov_b32 m0, s41
	v_lshl_add_u64 v[226:227], s[34:35], 0, v[132:133]
	global_load_lds_dwordx4 v[226:227], off
	s_setprio 1
	s_barrier
	s_waitcnt lgkmcnt(0)
	v_mfma_f32_16x16x32_bf16 v[60:63], v[144:147], v[168:171], v[60:63]
	v_mfma_f32_16x16x32_bf16 v[56:59], v[160:163], v[168:171], v[56:59]
	v_mfma_f32_16x16x32_bf16 v[44:47], v[144:147], v[180:183], v[44:47]
	v_mfma_f32_16x16x32_bf16 v[40:43], v[160:163], v[180:183], v[40:43]
	v_mfma_f32_16x16x32_bf16 v[28:31], v[144:147], v[188:191], v[28:31]
	v_mfma_f32_16x16x32_bf16 v[24:27], v[160:163], v[188:191], v[24:27]
	v_mfma_f32_16x16x32_bf16 v[12:15], v[144:147], v[196:199], v[12:15]
	v_mfma_f32_16x16x32_bf16 v[8:11], v[160:163], v[196:199], v[8:11]
	v_mfma_f32_16x16x32_bf16 v[60:63], v[156:159], v[176:179], v[60:63]
	v_mfma_f32_16x16x32_bf16 v[56:59], v[164:167], v[176:179], v[56:59]
	v_mfma_f32_16x16x32_bf16 v[44:47], v[156:159], v[184:187], v[44:47]
	v_mfma_f32_16x16x32_bf16 v[40:43], v[164:167], v[184:187], v[40:43]
	v_mfma_f32_16x16x32_bf16 v[28:31], v[156:159], v[192:195], v[28:31]
	v_mfma_f32_16x16x32_bf16 v[24:27], v[164:167], v[192:195], v[24:27]
	v_mfma_f32_16x16x32_bf16 v[12:15], v[156:159], v[200:203], v[12:15]
	v_mfma_f32_16x16x32_bf16 v[8:11], v[164:167], v[200:203], v[8:11]
	s_barrier
	s_setprio 0
	s_add_u32 s64, s30, 0x40000
	s_addc_u32 s65, s31, 0
	s_add_i32 s66, s53, s39
	s_mov_b32 m0, s66
	v_lshl_add_u64 v[144:145], s[64:65], 0, v[130:131]
	global_load_lds_dwordx4 v[144:145], off
	s_add_i32 m0, s66, 0x2000
	v_lshl_add_u64 v[144:145], s[64:65], 0, v[134:135]
	global_load_lds_dwordx4 v[144:145], off
	s_waitcnt vmcnt(6)
	s_setprio 1
	s_barrier
	v_mfma_f32_16x16x32_bf16 v[52:55], v[204:207], v[168:171], v[52:55]
	v_mfma_f32_16x16x32_bf16 v[48:51], v[216:219], v[168:171], v[48:51]
	v_mfma_f32_16x16x32_bf16 v[36:39], v[204:207], v[180:183], v[36:39]
	v_mfma_f32_16x16x32_bf16 v[32:35], v[216:219], v[180:183], v[32:35]
	v_mfma_f32_16x16x32_bf16 v[20:23], v[204:207], v[188:191], v[20:23]
	v_mfma_f32_16x16x32_bf16 v[16:19], v[216:219], v[188:191], v[16:19]
	v_mfma_f32_16x16x32_bf16 v[4:7], v[204:207], v[196:199], v[4:7]
	v_mfma_f32_16x16x32_bf16 v[0:3], v[216:219], v[196:199], v[0:3]
	v_mfma_f32_16x16x32_bf16 v[52:55], v[212:215], v[176:179], v[52:55]
	v_mfma_f32_16x16x32_bf16 v[48:51], v[220:223], v[176:179], v[48:51]
	v_mfma_f32_16x16x32_bf16 v[36:39], v[212:215], v[184:187], v[36:39]
	v_mfma_f32_16x16x32_bf16 v[32:35], v[220:223], v[184:187], v[32:35]
	v_mfma_f32_16x16x32_bf16 v[20:23], v[212:215], v[192:195], v[20:23]
	v_mfma_f32_16x16x32_bf16 v[16:19], v[220:223], v[192:195], v[16:19]
	v_mfma_f32_16x16x32_bf16 v[4:7], v[212:215], v[200:203], v[4:7]
	v_mfma_f32_16x16x32_bf16 v[0:3], v[220:223], v[200:203], v[0:3]
	s_barrier
	s_setprio 0
	s_add_i32 s64, 0, 0x18000
	v_add_u32_e32 v155, s64, v149
	ds_read_b128 v[144:147], v155
	ds_read_b128 v[156:159], v155 offset:1024
	ds_read_b128 v[160:163], v155 offset:2048
	ds_read_b128 v[164:167], v155 offset:3072
	s_add_u32 s34, s34, 0x40000
	s_addc_u32 s35, s35, 0
	s_mov_b32 m0, s42
	v_lshl_add_u64 v[204:205], s[34:35], 0, v[128:129]
	ds_read_b128 v[168:171], v152 offset:32768
	ds_read_b128 v[176:179], v152 offset:33792
	ds_read_b128 v[180:183], v152 offset:34816
	ds_read_b128 v[184:187], v152 offset:35840
	ds_read_b128 v[188:191], v152 offset:36864
	ds_read_b128 v[192:195], v152 offset:37888
	ds_read_b128 v[196:199], v152 offset:38912
	ds_read_b128 v[200:203], v152 offset:39936
	global_load_lds_dwordx4 v[204:205], off
	s_mov_b32 m0, s43
	v_lshl_add_u64 v[204:205], s[34:35], 0, v[132:133]
	global_load_lds_dwordx4 v[204:205], off
	s_waitcnt lgkmcnt(8)
	s_setprio 1
	s_barrier
	s_waitcnt lgkmcnt(0)
	v_mfma_f32_16x16x32_bf16 v[124:127], v[144:147], v[168:171], v[124:127]
	v_mfma_f32_16x16x32_bf16 v[120:123], v[160:163], v[168:171], v[120:123]
	v_mfma_f32_16x16x32_bf16 v[116:119], v[144:147], v[180:183], v[116:119]
	v_mfma_f32_16x16x32_bf16 v[112:115], v[160:163], v[180:183], v[112:115]
	v_mfma_f32_16x16x32_bf16 v[92:95], v[144:147], v[188:191], v[92:95]
	v_mfma_f32_16x16x32_bf16 v[88:91], v[160:163], v[188:191], v[88:91]
	v_mfma_f32_16x16x32_bf16 v[76:79], v[144:147], v[196:199], v[76:79]
	v_mfma_f32_16x16x32_bf16 v[72:75], v[160:163], v[196:199], v[72:75]
	v_mfma_f32_16x16x32_bf16 v[124:127], v[156:159], v[176:179], v[124:127]
	v_mfma_f32_16x16x32_bf16 v[120:123], v[164:167], v[176:179], v[120:123]
	v_mfma_f32_16x16x32_bf16 v[116:119], v[156:159], v[184:187], v[116:119]
	v_mfma_f32_16x16x32_bf16 v[112:115], v[164:167], v[184:187], v[112:115]
	v_mfma_f32_16x16x32_bf16 v[92:95], v[156:159], v[192:195], v[92:95]
	v_mfma_f32_16x16x32_bf16 v[88:91], v[164:167], v[192:195], v[88:91]
	v_mfma_f32_16x16x32_bf16 v[76:79], v[156:159], v[200:203], v[76:79]
	v_mfma_f32_16x16x32_bf16 v[72:75], v[164:167], v[200:203], v[72:75]
	s_barrier
	s_setprio 0
	s_add_i32 s34, 0, 0x1c000
	s_add_i32 s35, s64, s39
	v_add_u32_e32 v155, s34, v149
	v_lshl_add_u64 v[172:173], v[172:173], 0, s[6:7]
	s_mov_b32 m0, s35
	ds_read_b128 v[204:207], v155
	ds_read_b128 v[212:215], v155 offset:1024
	ds_read_b128 v[216:219], v155 offset:2048
	ds_read_b128 v[220:223], v155 offset:3072
	global_load_lds_dwordx4 v[172:173], off
	s_add_i32 m0, s35, 0x2000
	v_lshl_add_u64 v[172:173], v[208:209], 0, s[6:7]
	global_load_lds_dwordx4 v[172:173], off
	s_setprio 1
	s_barrier
	s_waitcnt lgkmcnt(0)
	v_mfma_f32_16x16x32_bf16 v[108:111], v[204:207], v[168:171], v[108:111]
	v_mfma_f32_16x16x32_bf16 v[104:107], v[216:219], v[168:171], v[104:107]
	v_mfma_f32_16x16x32_bf16 v[100:103], v[204:207], v[180:183], v[100:103]
	v_mfma_f32_16x16x32_bf16 v[96:99], v[216:219], v[180:183], v[96:99]
	v_mfma_f32_16x16x32_bf16 v[84:87], v[204:207], v[188:191], v[84:87]
	v_mfma_f32_16x16x32_bf16 v[80:83], v[216:219], v[188:191], v[80:83]
	v_mfma_f32_16x16x32_bf16 v[68:71], v[204:207], v[196:199], v[68:71]
	v_mfma_f32_16x16x32_bf16 v[64:67], v[216:219], v[196:199], v[64:67]
	v_mfma_f32_16x16x32_bf16 v[108:111], v[212:215], v[176:179], v[108:111]
	v_mfma_f32_16x16x32_bf16 v[104:107], v[220:223], v[176:179], v[104:107]
	v_mfma_f32_16x16x32_bf16 v[100:103], v[212:215], v[184:187], v[100:103]
	v_mfma_f32_16x16x32_bf16 v[96:99], v[220:223], v[184:187], v[96:99]
	v_mfma_f32_16x16x32_bf16 v[84:87], v[212:215], v[192:195], v[84:87]
	v_mfma_f32_16x16x32_bf16 v[80:83], v[220:223], v[192:195], v[80:83]
	v_mfma_f32_16x16x32_bf16 v[68:71], v[212:215], v[200:203], v[68:71]
	v_mfma_f32_16x16x32_bf16 v[64:67], v[220:223], v[200:203], v[64:67]
	s_barrier
	s_setprio 0
	s_mov_b32 m0, s49
	v_lshl_add_u64 v[172:173], v[224:225], 0, s[6:7]
	ds_read_b128 v[168:171], v152 offset:49152
	ds_read_b128 v[176:179], v152 offset:50176
	ds_read_b128 v[180:183], v152 offset:51200
	ds_read_b128 v[184:187], v152 offset:52224
	ds_read_b128 v[188:191], v152 offset:53248
	ds_read_b128 v[192:195], v152 offset:54272
	ds_read_b128 v[196:199], v152 offset:55296
	ds_read_b128 v[200:203], v152 offset:56320
	global_load_lds_dwordx4 v[172:173], off
	s_mov_b32 m0, s50
	v_lshl_add_u64 v[172:173], v[226:227], 0, s[6:7]
	global_load_lds_dwordx4 v[172:173], off
	s_setprio 1
	s_barrier
	s_waitcnt lgkmcnt(0)
	v_mfma_f32_16x16x32_bf16 v[60:63], v[144:147], v[168:171], v[60:63]
	v_mfma_f32_16x16x32_bf16 v[56:59], v[160:163], v[168:171], v[56:59]
	v_mfma_f32_16x16x32_bf16 v[44:47], v[144:147], v[180:183], v[44:47]
	v_mfma_f32_16x16x32_bf16 v[40:43], v[160:163], v[180:183], v[40:43]
	v_mfma_f32_16x16x32_bf16 v[28:31], v[144:147], v[188:191], v[28:31]
	v_mfma_f32_16x16x32_bf16 v[24:27], v[160:163], v[188:191], v[24:27]
	v_mfma_f32_16x16x32_bf16 v[12:15], v[144:147], v[196:199], v[12:15]
	v_mfma_f32_16x16x32_bf16 v[8:11], v[160:163], v[196:199], v[8:11]
	v_mfma_f32_16x16x32_bf16 v[60:63], v[156:159], v[176:179], v[60:63]
	v_mfma_f32_16x16x32_bf16 v[56:59], v[164:167], v[176:179], v[56:59]
	v_mfma_f32_16x16x32_bf16 v[44:47], v[156:159], v[184:187], v[44:47]
	v_mfma_f32_16x16x32_bf16 v[40:43], v[164:167], v[184:187], v[40:43]
	v_mfma_f32_16x16x32_bf16 v[28:31], v[156:159], v[192:195], v[28:31]
	v_mfma_f32_16x16x32_bf16 v[24:27], v[164:167], v[192:195], v[24:27]
	v_mfma_f32_16x16x32_bf16 v[12:15], v[156:159], v[200:203], v[12:15]
	v_mfma_f32_16x16x32_bf16 v[8:11], v[164:167], v[200:203], v[8:11]
	s_barrier
	s_setprio 0
	s_add_u32 s30, s30, 0x40080
	s_addc_u32 s31, s31, 0
	s_add_i32 s34, s34, s39
	s_mov_b32 m0, s34
	v_lshl_add_u64 v[144:145], s[30:31], 0, v[130:131]
	global_load_lds_dwordx4 v[144:145], off
	s_add_i32 m0, s34, 0x2000
	v_lshl_add_u64 v[144:145], s[30:31], 0, v[134:135]
	global_load_lds_dwordx4 v[144:145], off
	s_waitcnt vmcnt(6)
	s_setprio 1
	s_barrier
	v_mfma_f32_16x16x32_bf16 v[52:55], v[204:207], v[168:171], v[52:55]
	v_mfma_f32_16x16x32_bf16 v[48:51], v[216:219], v[168:171], v[48:51]
	v_mfma_f32_16x16x32_bf16 v[36:39], v[204:207], v[180:183], v[36:39]
	v_mfma_f32_16x16x32_bf16 v[32:35], v[216:219], v[180:183], v[32:35]
	v_mfma_f32_16x16x32_bf16 v[20:23], v[204:207], v[188:191], v[20:23]
	v_mfma_f32_16x16x32_bf16 v[16:19], v[216:219], v[188:191], v[16:19]
	v_mfma_f32_16x16x32_bf16 v[4:7], v[204:207], v[196:199], v[4:7]
	v_mfma_f32_16x16x32_bf16 v[0:3], v[216:219], v[196:199], v[0:3]
	v_mfma_f32_16x16x32_bf16 v[52:55], v[212:215], v[176:179], v[52:55]
	v_mfma_f32_16x16x32_bf16 v[48:51], v[220:223], v[176:179], v[48:51]
	v_mfma_f32_16x16x32_bf16 v[36:39], v[212:215], v[184:187], v[36:39]
	v_mfma_f32_16x16x32_bf16 v[32:35], v[220:223], v[184:187], v[32:35]
	v_mfma_f32_16x16x32_bf16 v[20:23], v[212:215], v[192:195], v[20:23]
	v_mfma_f32_16x16x32_bf16 v[16:19], v[220:223], v[192:195], v[16:19]
	v_mfma_f32_16x16x32_bf16 v[4:7], v[212:215], v[200:203], v[4:7]
	v_mfma_f32_16x16x32_bf16 v[0:3], v[220:223], v[200:203], v[0:3]
	s_barrier
	s_setprio 0
	s_add_i32 s63, s63, 2
	s_add_u32 s28, s28, 0x100
	s_addc_u32 s29, s29, 0
	s_add_u32 s61, s61, 0x100
	s_addc_u32 s62, s62, 0
	s_cmp_gt_u32 s63, 13
	s_cbranch_scc0 .LBB0_1218
	v_lshl_add_u32 v146, s0, 8, v148
	v_ashrrev_i32_e32 v147, 31, v146
	v_mov_b32_e32 v155, v242
	v_mov_b32_e32 v162, v243
	v_mov_b32_e32 v163, v244
	v_mov_b32_e32 v164, v245
	v_mov_b32_e32 v165, v246
	v_mov_b32_e32 v166, v247
	v_mov_b32_e32 v167, v248
	v_mov_b32_e32 v168, v249
	v_lshl_or_b32 v144, s1, 8, v150
	v_ashrrev_i32_e32 v145, 31, v144
	v_lshlrev_b64 v[158:159], 13, v[146:147]
	v_lshlrev_b64 v[160:161], 1, v[144:145]
	v_lshl_add_u64 v[144:145], s[92:93], 0, v[158:159]
	v_lshl_add_u64 v[144:145], v[144:145], 0, v[160:161]
	v_or_b32_e32 v156, 16, v146
	v_ashrrev_i32_e32 v157, 31, v156
	v_lshlrev_b64 v[156:157], 13, v[156:157]
	v_lshl_add_u64 v[156:157], s[92:93], 0, v[156:157]
	v_lshl_add_u64 v[156:157], v[156:157], 0, v[160:161]
	s_mov_b64 s[30:31], s[26:27]
	s_mov_b64 s[28:29], s[24:25]
	v_fmamk_f32 v147, v155, 0x3a800000, v154
	v_mul_f32_e32 v158, 0x4b800000, v147
	v_cmp_gt_f32_e32 vcc, s54, v147
	v_fmamk_f32 v155, v162, 0x3a800000, v154
	v_mul_f32_e32 v162, 0x4b800000, v155
	v_cndmask_b32_e32 v147, v147, v158, vcc
	v_rsq_f32_e32 v158, v147
	v_cmp_gt_f32_e64 s[0:1], s54, v155
	v_fmamk_f32 v159, v163, 0x3a800000, v154
	v_fmamk_f32 v163, v164, 0x3a800000, v154
	v_cndmask_b32_e64 v155, v155, v162, s[0:1]
	v_rsq_f32_e32 v155, v155
	v_mul_f32_e32 v162, 0x45800000, v158
	v_cndmask_b32_e32 v158, v158, v162, vcc
	v_pk_mul_f32 v[124:125], v[124:125], v[158:159] op_sel_hi:[1,0]
	v_pk_mul_f32 v[104:105], v[104:105], v[158:159] op_sel_hi:[1,0]
	v_fmamk_f32 v164, v165, 0x3a800000, v154
	v_fmamk_f32 v165, v166, 0x3a800000, v154
	v_fmamk_f32 v166, v167, 0x3a800000, v154
	v_mul_f32_e32 v167, 0x45800000, v155
	v_pk_mul_f32 v[126:127], v[126:127], v[158:159] op_sel_hi:[1,0]
	v_pk_mul_f32 v[122:123], v[122:123], v[158:159] op_sel_hi:[1,0]
	v_pk_mul_f32 v[120:121], v[120:121], v[158:159] op_sel_hi:[1,0]
	v_pk_mul_f32 v[108:109], v[108:109], v[158:159] op_sel_hi:[1,0]
	v_pk_mul_f32 v[106:107], v[106:107], v[158:159] op_sel_hi:[1,0]
	v_max_f32_e32 v124, 0, v124
	v_max_f32_e32 v125, 0, v125
	v_max_f32_e32 v104, 0, v104
	v_cndmask_b32_e64 v162, v155, v167, s[0:1]
	v_pk_mul_f32 v[110:111], v[110:111], v[158:159] op_sel_hi:[1,0]
	v_max_f32_e32 v120, 0, v120
	v_max_f32_e32 v121, 0, v121
	v_max_f32_e32 v126, 0, v126
	v_max_f32_e32 v122, 0, v122
	v_max_f32_e32 v127, 0, v127
	v_max_f32_e32 v123, 0, v123
	v_max_f32_e32 v108, 0, v108
	v_max_f32_e32 v109, 0, v109
	v_max_f32_e32 v105, 0, v105
	v_max_f32_e32 v106, 0, v106
	v_max_f32_e32 v107, 0, v107
	v_pk_mul_f32 v[124:125], v[124:125], v[124:125]
	v_mul_f32_e32 v155, v104, v104
	v_cvt_pk_bf16_f32 v104, v124, v125
	v_fmamk_f32 v147, v168, 0x3a800000, v154
	v_pk_mul_f32 v[112:113], v[112:113], v[162:163] op_sel_hi:[1,0]
	v_max_f32_e32 v110, 0, v110
	v_max_f32_e32 v111, 0, v111
	v_pk_mul_f32 v[120:121], v[120:121], v[120:121]
	v_pk_mul_f32 v[126:127], v[126:127], v[126:127]
	v_pk_mul_f32 v[122:123], v[122:123], v[122:123]
	v_pk_mul_f32 v[108:109], v[108:109], v[108:109]
	v_mul_f32_e32 v158, v105, v105
	v_mul_f32_e32 v167, v106, v106
	v_mul_f32_e32 v168, v107, v107
	v_cvt_pk_bf16_f32 v105, v126, v127
	v_cvt_pk_bf16_f32 v106, v120, v121
	v_cvt_pk_bf16_f32 v107, v122, v123
	global_store_dwordx4 v[144:145], v[104:107], off nt
	v_pk_mul_f32 v[116:117], v[116:117], v[162:163] op_sel_hi:[1,0]
	v_pk_mul_f32 v[110:111], v[110:111], v[110:111]
	v_cvt_pk_bf16_f32 v104, v108, v109
	v_cvt_pk_bf16_f32 v105, v110, v111
	v_cvt_pk_bf16_f32 v106, v155, v158
	v_cvt_pk_bf16_f32 v107, v167, v168
	global_store_dwordx4 v[144:145], v[104:107], off offset:256 nt
	v_pk_mul_f32 v[118:119], v[118:119], v[162:163] op_sel_hi:[1,0]
	v_pk_mul_f32 v[114:115], v[114:115], v[162:163] op_sel_hi:[1,0]
	v_max_f32_e32 v104, 0, v112
	v_mul_f32_e32 v106, v104, v104
	v_max_f32_e32 v104, 0, v117
	v_max_f32_e32 v116, 0, v116
	v_max_f32_e32 v107, 0, v113
	v_mul_f32_e32 v104, v104, v104
	v_pk_mul_f32 v[98:99], v[98:99], v[162:163] op_sel_hi:[1,0]
	v_pk_mul_f32 v[96:97], v[96:97], v[162:163] op_sel_hi:[1,0]
	v_mul_f32_e32 v105, v116, v116
	v_mul_f32_e32 v107, v107, v107
	v_max_f32_e32 v108, 0, v118
	v_max_f32_e32 v109, 0, v114
	v_max_f32_e32 v110, 0, v119
	v_max_f32_e32 v111, 0, v115
	v_cvt_pk_bf16_f32 v104, v105, v104
	v_pk_mul_f32 v[102:103], v[102:103], v[162:163] op_sel_hi:[1,0]
	v_pk_mul_f32 v[100:101], v[100:101], v[162:163] op_sel_hi:[1,0]
	v_max_f32_e32 v96, 0, v96
	v_max_f32_e32 v97, 0, v97
	v_max_f32_e32 v98, 0, v98
	v_pk_mul_f32 v[108:109], v[108:109], v[108:109]
	v_pk_mul_f32 v[110:111], v[110:111], v[110:111]
	v_cvt_pk_bf16_f32 v105, v108, v110
	v_cvt_pk_bf16_f32 v106, v106, v107
	v_cvt_pk_bf16_f32 v107, v109, v111
	global_store_dwordx4 v[156:157], v[104:107], off nt
	v_max_f32_e32 v100, 0, v100
	v_max_f32_e32 v99, 0, v99
	v_mul_f32_e32 v104, v96, v96
	v_max_f32_e32 v96, 0, v101
	v_mul_f32_e32 v101, v97, v97
	v_max_f32_e32 v97, 0, v102
	v_mul_f32_e32 v102, v98, v98
	v_max_f32_e32 v98, 0, v103
	v_pk_mul_f32 v[96:97], v[96:97], v[96:97]
	v_pk_mul_f32 v[98:99], v[98:99], v[98:99]
	v_mul_f32_e32 v100, v100, v100
	v_cvt_pk_bf16_f32 v96, v100, v96
	v_cvt_pk_bf16_f32 v97, v97, v98
	v_cvt_pk_bf16_f32 v98, v104, v101
	v_cvt_pk_bf16_f32 v99, v102, v99
	global_store_dwordx4 v[156:157], v[96:99], off offset:256 nt
	v_cmp_gt_f32_e32 vcc, s54, v159
	s_mov_b32 s1, s20
	v_mul_f32_e32 v98, 0x4b800000, v159
	v_cndmask_b32_e32 v98, v159, v98, vcc
	v_rsq_f32_e32 v98, v98
	v_or_b32_e32 v96, 32, v146
	v_ashrrev_i32_e32 v97, 31, v96
	v_lshlrev_b64 v[96:97], 13, v[96:97]
	v_mul_f32_e32 v99, 0x45800000, v98
	v_cndmask_b32_e32 v98, v98, v99, vcc
	v_pk_mul_f32 v[88:89], v[88:89], v[98:99] op_sel_hi:[1,0]
	v_pk_mul_f32 v[92:93], v[92:93], v[98:99] op_sel_hi:[1,0]
	v_pk_mul_f32 v[90:91], v[90:91], v[98:99] op_sel_hi:[1,0]
	v_max_f32_e32 v88, 0, v88
	v_pk_mul_f32 v[94:95], v[94:95], v[98:99] op_sel_hi:[1,0]
	v_mul_f32_e32 v99, v88, v88
	v_max_f32_e32 v88, 0, v93
	v_max_f32_e32 v89, 0, v89
	v_max_f32_e32 v90, 0, v90
	v_lshl_add_u64 v[96:97], s[92:93], 0, v[96:97]
	v_max_f32_e32 v92, 0, v92
	v_mul_f32_e32 v88, v88, v88
	v_mul_f32_e32 v93, v89, v89
	v_max_f32_e32 v89, 0, v94
	v_mul_f32_e32 v94, v90, v90
	v_max_f32_e32 v90, 0, v95
	v_max_f32_e32 v91, 0, v91
	v_pk_mul_f32 v[82:83], v[82:83], v[98:99] op_sel_hi:[1,0]
	v_pk_mul_f32 v[80:81], v[80:81], v[98:99] op_sel_hi:[1,0]
	v_lshl_add_u64 v[96:97], v[96:97], 0, v[160:161]
	v_mul_f32_e32 v92, v92, v92
	v_mul_f32_e32 v89, v89, v89
	v_pk_mul_f32 v[90:91], v[90:91], v[90:91]
	v_cvt_pk_bf16_f32 v88, v92, v88
	v_pk_mul_f32 v[86:87], v[86:87], v[98:99] op_sel_hi:[1,0]
	v_pk_mul_f32 v[84:85], v[84:85], v[98:99] op_sel_hi:[1,0]
	v_max_f32_e32 v80, 0, v80
	v_max_f32_e32 v81, 0, v81
	v_max_f32_e32 v82, 0, v82
	v_cvt_pk_bf16_f32 v89, v89, v90
	v_cvt_pk_bf16_f32 v90, v99, v93
	v_cvt_pk_bf16_f32 v91, v94, v91
	global_store_dwordx4 v[96:97], v[88:91], off nt
	v_max_f32_e32 v84, 0, v84
	v_max_f32_e32 v83, 0, v83
	v_mul_f32_e32 v88, v80, v80
	v_max_f32_e32 v80, 0, v85
	v_mul_f32_e32 v85, v81, v81
	v_max_f32_e32 v81, 0, v86
	v_mul_f32_e32 v86, v82, v82
	v_max_f32_e32 v82, 0, v87
	v_pk_mul_f32 v[80:81], v[80:81], v[80:81]
	v_pk_mul_f32 v[82:83], v[82:83], v[82:83]
	v_mul_f32_e32 v84, v84, v84
	v_cvt_pk_bf16_f32 v80, v84, v80
	v_cvt_pk_bf16_f32 v81, v81, v82
	v_cvt_pk_bf16_f32 v82, v88, v85
	v_cvt_pk_bf16_f32 v83, v86, v83
	global_store_dwordx4 v[96:97], v[80:83], off offset:256 nt
	v_cmp_gt_f32_e32 vcc, s54, v163
	s_mov_b32 s0, s22
	v_mul_f32_e32 v82, 0x4b800000, v163
	v_cndmask_b32_e32 v82, v163, v82, vcc
	v_rsq_f32_e32 v82, v82
	v_or_b32_e32 v80, 48, v146
	v_ashrrev_i32_e32 v81, 31, v80
	v_lshlrev_b64 v[80:81], 13, v[80:81]
	v_mul_f32_e32 v83, 0x45800000, v82
	v_cndmask_b32_e32 v82, v82, v83, vcc
	v_pk_mul_f32 v[72:73], v[72:73], v[82:83] op_sel_hi:[1,0]
	v_pk_mul_f32 v[76:77], v[76:77], v[82:83] op_sel_hi:[1,0]
	v_pk_mul_f32 v[74:75], v[74:75], v[82:83] op_sel_hi:[1,0]
	v_max_f32_e32 v72, 0, v72
	v_pk_mul_f32 v[78:79], v[78:79], v[82:83] op_sel_hi:[1,0]
	v_mul_f32_e32 v83, v72, v72
	v_max_f32_e32 v72, 0, v77
	v_max_f32_e32 v73, 0, v73
	v_max_f32_e32 v74, 0, v74
	v_lshl_add_u64 v[80:81], s[92:93], 0, v[80:81]
	v_max_f32_e32 v76, 0, v76
	v_mul_f32_e32 v72, v72, v72
	v_mul_f32_e32 v77, v73, v73
	v_max_f32_e32 v73, 0, v78
	v_mul_f32_e32 v78, v74, v74
	v_max_f32_e32 v74, 0, v79
	v_max_f32_e32 v75, 0, v75
	v_pk_mul_f32 v[64:65], v[64:65], v[82:83] op_sel_hi:[1,0]
	v_lshl_add_u64 v[80:81], v[80:81], 0, v[160:161]
	v_mul_f32_e32 v76, v76, v76
	v_mul_f32_e32 v73, v73, v73
	v_pk_mul_f32 v[74:75], v[74:75], v[74:75]
	v_cvt_pk_bf16_f32 v72, v76, v72
	v_pk_mul_f32 v[68:69], v[68:69], v[82:83] op_sel_hi:[1,0]
	v_max_f32_e32 v64, 0, v64
	v_cvt_pk_bf16_f32 v73, v73, v74
	v_cvt_pk_bf16_f32 v74, v83, v77
	v_cvt_pk_bf16_f32 v75, v78, v75
	global_store_dwordx4 v[80:81], v[72:75], off nt
	v_max_f32_e32 v68, 0, v68
	v_mul_f32_e32 v68, v68, v68
	v_mul_f32_e32 v72, v64, v64
	v_max_f32_e32 v64, 0, v69
	v_mul_f32_e32 v64, v64, v64
	v_cvt_pk_bf16_f32 v64, v68, v64
	v_mul_f32_e32 v68, 0x4b800000, v164
	v_cmp_gt_f32_e32 vcc, s54, v164
	v_pk_mul_f32 v[66:67], v[66:67], v[82:83] op_sel_hi:[1,0]
	v_pk_mul_f32 v[70:71], v[70:71], v[82:83] op_sel_hi:[1,0]
	v_cndmask_b32_e32 v68, v164, v68, vcc
	v_max_f32_e32 v65, 0, v65
	v_max_f32_e32 v66, 0, v66
	v_rsq_f32_e32 v68, v68
	v_mul_f32_e32 v69, v65, v65
	v_max_f32_e32 v65, 0, v70
	v_mul_f32_e32 v70, v66, v66
	v_max_f32_e32 v66, 0, v71
	v_mul_f32_e32 v65, v65, v65
	v_max_f32_e32 v67, 0, v67
	v_pk_mul_f32 v[66:67], v[66:67], v[66:67]
	v_cvt_pk_bf16_f32 v65, v65, v66
	v_cvt_pk_bf16_f32 v66, v72, v69
	v_cvt_pk_bf16_f32 v67, v70, v67
	global_store_dwordx4 v[80:81], v[64:67], off offset:256 nt
	s_nop 1
	v_mul_f32_e32 v66, 0x45800000, v68
	v_cndmask_b32_e32 v66, v68, v66, vcc
	v_pk_mul_f32 v[56:57], v[56:57], v[66:67] op_sel_hi:[1,0]
	v_pk_mul_f32 v[60:61], v[60:61], v[66:67] op_sel_hi:[1,0]
	v_pk_mul_f32 v[58:59], v[58:59], v[66:67] op_sel_hi:[1,0]
	v_max_f32_e32 v56, 0, v56
	v_pk_mul_f32 v[62:63], v[62:63], v[66:67] op_sel_hi:[1,0]
	v_max_f32_e32 v60, 0, v60
	v_mul_f32_e32 v67, v56, v56
	v_max_f32_e32 v56, 0, v61
	v_max_f32_e32 v57, 0, v57
	v_max_f32_e32 v58, 0, v58
	v_mul_f32_e32 v60, v60, v60
	v_mul_f32_e32 v56, v56, v56
	v_mul_f32_e32 v61, v57, v57
	v_max_f32_e32 v57, 0, v62
	v_mul_f32_e32 v62, v58, v58
	v_max_f32_e32 v58, 0, v63
	v_mul_f32_e32 v57, v57, v57
	v_max_f32_e32 v59, 0, v59
	v_pk_mul_f32 v[58:59], v[58:59], v[58:59]
	v_cvt_pk_bf16_f32 v56, v60, v56
	v_add_co_u32_e32 v60, vcc, s55, v144
	v_pk_mul_f32 v[48:49], v[48:49], v[66:67] op_sel_hi:[1,0]
	v_cvt_pk_bf16_f32 v57, v57, v58
	v_cvt_pk_bf16_f32 v58, v67, v61
	v_addc_co_u32_e32 v61, vcc, 0, v145, vcc
	v_pk_mul_f32 v[52:53], v[52:53], v[66:67] op_sel_hi:[1,0]
	v_max_f32_e32 v48, 0, v48
	v_cvt_pk_bf16_f32 v59, v62, v59
	global_store_dwordx4 v[60:61], v[56:59], off nt
	v_max_f32_e32 v52, 0, v52
	v_mul_f32_e32 v52, v52, v52
	v_mul_f32_e32 v56, v48, v48
	v_max_f32_e32 v48, 0, v53
	v_mul_f32_e32 v48, v48, v48
	v_cvt_pk_bf16_f32 v48, v52, v48
	v_mul_f32_e32 v52, 0x4b800000, v165
	v_cmp_gt_f32_e32 vcc, s54, v165
	v_pk_mul_f32 v[50:51], v[50:51], v[66:67] op_sel_hi:[1,0]
	v_pk_mul_f32 v[54:55], v[54:55], v[66:67] op_sel_hi:[1,0]
	v_cndmask_b32_e32 v52, v165, v52, vcc
	v_max_f32_e32 v49, 0, v49
	v_max_f32_e32 v50, 0, v50
	v_rsq_f32_e32 v52, v52
	v_mul_f32_e32 v53, v49, v49
	v_max_f32_e32 v49, 0, v54
	v_mul_f32_e32 v54, v50, v50
	v_max_f32_e32 v50, 0, v55
	v_mul_f32_e32 v49, v49, v49
	v_max_f32_e32 v51, 0, v51
	v_pk_mul_f32 v[50:51], v[50:51], v[50:51]
	v_lshl_add_u64 v[64:65], v[144:145], 0, s[12:13]
	v_cvt_pk_bf16_f32 v49, v49, v50
	v_cvt_pk_bf16_f32 v50, v56, v53
	v_cvt_pk_bf16_f32 v51, v54, v51
	global_store_dwordx4 v[64:65], v[48:51], off offset:256 nt
	s_nop 1
	v_mul_f32_e32 v50, 0x45800000, v52
	v_cndmask_b32_e32 v50, v52, v50, vcc
	v_pk_mul_f32 v[40:41], v[40:41], v[50:51] op_sel_hi:[1,0]
	v_pk_mul_f32 v[44:45], v[44:45], v[50:51] op_sel_hi:[1,0]
	v_pk_mul_f32 v[42:43], v[42:43], v[50:51] op_sel_hi:[1,0]
	v_max_f32_e32 v40, 0, v40
	v_pk_mul_f32 v[46:47], v[46:47], v[50:51] op_sel_hi:[1,0]
	v_max_f32_e32 v44, 0, v44
	v_mul_f32_e32 v51, v40, v40
	v_max_f32_e32 v40, 0, v45
	v_max_f32_e32 v41, 0, v41
	v_max_f32_e32 v42, 0, v42
	v_mul_f32_e32 v44, v44, v44
	v_mul_f32_e32 v40, v40, v40
	v_mul_f32_e32 v45, v41, v41
	v_max_f32_e32 v41, 0, v46
	v_mul_f32_e32 v46, v42, v42
	v_max_f32_e32 v42, 0, v47
	v_mul_f32_e32 v41, v41, v41
	v_max_f32_e32 v43, 0, v43
	v_pk_mul_f32 v[42:43], v[42:43], v[42:43]
	v_cvt_pk_bf16_f32 v40, v44, v40
	v_add_co_u32_e32 v44, vcc, s56, v144
	v_pk_mul_f32 v[32:33], v[32:33], v[50:51] op_sel_hi:[1,0]
	v_cvt_pk_bf16_f32 v41, v41, v42
	v_cvt_pk_bf16_f32 v42, v51, v45
	v_addc_co_u32_e32 v45, vcc, 0, v145, vcc
	v_pk_mul_f32 v[36:37], v[36:37], v[50:51] op_sel_hi:[1,0]
	v_max_f32_e32 v32, 0, v32
	v_cvt_pk_bf16_f32 v43, v46, v43
	global_store_dwordx4 v[44:45], v[40:43], off nt
	v_max_f32_e32 v36, 0, v36
	v_mul_f32_e32 v36, v36, v36
	v_mul_f32_e32 v40, v32, v32
	v_max_f32_e32 v32, 0, v37
	v_mul_f32_e32 v32, v32, v32
	v_cvt_pk_bf16_f32 v32, v36, v32
	v_mul_f32_e32 v36, 0x4b800000, v166
	v_cmp_gt_f32_e32 vcc, s54, v166
	v_pk_mul_f32 v[34:35], v[34:35], v[50:51] op_sel_hi:[1,0]
	v_pk_mul_f32 v[38:39], v[38:39], v[50:51] op_sel_hi:[1,0]
	v_cndmask_b32_e32 v36, v166, v36, vcc
	v_max_f32_e32 v33, 0, v33
	v_max_f32_e32 v34, 0, v34
	v_rsq_f32_e32 v36, v36
	v_mul_f32_e32 v37, v33, v33
	v_max_f32_e32 v33, 0, v38
	v_mul_f32_e32 v38, v34, v34
	v_max_f32_e32 v34, 0, v39
	v_mul_f32_e32 v33, v33, v33
	v_max_f32_e32 v35, 0, v35
	v_pk_mul_f32 v[34:35], v[34:35], v[34:35]
	v_lshl_add_u64 v[48:49], v[144:145], 0, s[14:15]
	v_cvt_pk_bf16_f32 v33, v33, v34
	v_cvt_pk_bf16_f32 v34, v40, v37
	v_cvt_pk_bf16_f32 v35, v38, v35
	global_store_dwordx4 v[48:49], v[32:35], off offset:256 nt
	s_nop 1
	v_mul_f32_e32 v34, 0x45800000, v36
	v_cndmask_b32_e32 v34, v36, v34, vcc
	v_pk_mul_f32 v[24:25], v[24:25], v[34:35] op_sel_hi:[1,0]
	v_pk_mul_f32 v[28:29], v[28:29], v[34:35] op_sel_hi:[1,0]
	v_pk_mul_f32 v[26:27], v[26:27], v[34:35] op_sel_hi:[1,0]
	v_max_f32_e32 v24, 0, v24
	v_pk_mul_f32 v[30:31], v[30:31], v[34:35] op_sel_hi:[1,0]
	v_max_f32_e32 v28, 0, v28
	v_mul_f32_e32 v35, v24, v24
	v_max_f32_e32 v24, 0, v29
	v_max_f32_e32 v25, 0, v25
	v_max_f32_e32 v26, 0, v26
	v_mul_f32_e32 v28, v28, v28
	v_mul_f32_e32 v24, v24, v24
	v_mul_f32_e32 v29, v25, v25
	v_max_f32_e32 v25, 0, v30
	v_mul_f32_e32 v30, v26, v26
	v_max_f32_e32 v26, 0, v31
	v_mul_f32_e32 v25, v25, v25
	v_max_f32_e32 v27, 0, v27
	v_pk_mul_f32 v[26:27], v[26:27], v[26:27]
	v_cvt_pk_bf16_f32 v24, v28, v24
	v_add_co_u32_e32 v28, vcc, s57, v144
	v_pk_mul_f32 v[16:17], v[16:17], v[34:35] op_sel_hi:[1,0]
	v_cvt_pk_bf16_f32 v25, v25, v26
	v_cvt_pk_bf16_f32 v26, v35, v29
	v_addc_co_u32_e32 v29, vcc, 0, v145, vcc
	v_pk_mul_f32 v[20:21], v[20:21], v[34:35] op_sel_hi:[1,0]
	v_max_f32_e32 v16, 0, v16
	v_cvt_pk_bf16_f32 v27, v30, v27
	global_store_dwordx4 v[28:29], v[24:27], off nt
	v_max_f32_e32 v20, 0, v20
	v_mul_f32_e32 v20, v20, v20
	v_mul_f32_e32 v24, v16, v16
	v_max_f32_e32 v16, 0, v21
	v_mul_f32_e32 v16, v16, v16
	v_cvt_pk_bf16_f32 v16, v20, v16
	v_mul_f32_e32 v20, 0x4b800000, v147
	v_cmp_gt_f32_e32 vcc, s54, v147
	v_pk_mul_f32 v[18:19], v[18:19], v[34:35] op_sel_hi:[1,0]
	v_pk_mul_f32 v[22:23], v[22:23], v[34:35] op_sel_hi:[1,0]
	v_cndmask_b32_e32 v20, v147, v20, vcc
	v_max_f32_e32 v17, 0, v17
	v_max_f32_e32 v18, 0, v18
	v_rsq_f32_e32 v20, v20
	v_mul_f32_e32 v21, v17, v17
	v_max_f32_e32 v17, 0, v22
	v_mul_f32_e32 v22, v18, v18
	v_max_f32_e32 v18, 0, v23
	v_mul_f32_e32 v17, v17, v17
	v_max_f32_e32 v19, 0, v19
	v_pk_mul_f32 v[18:19], v[18:19], v[18:19]
	v_lshl_add_u64 v[32:33], v[144:145], 0, s[16:17]
	v_cvt_pk_bf16_f32 v17, v17, v18
	v_cvt_pk_bf16_f32 v18, v24, v21
	v_cvt_pk_bf16_f32 v19, v22, v19
	global_store_dwordx4 v[32:33], v[16:19], off offset:256 nt
	s_nop 1
	v_mul_f32_e32 v18, 0x45800000, v20
	v_cndmask_b32_e32 v18, v20, v18, vcc
	v_pk_mul_f32 v[8:9], v[8:9], v[18:19] op_sel_hi:[1,0]
	v_pk_mul_f32 v[12:13], v[12:13], v[18:19] op_sel_hi:[1,0]
	v_pk_mul_f32 v[10:11], v[10:11], v[18:19] op_sel_hi:[1,0]
	v_max_f32_e32 v8, 0, v8
	v_pk_mul_f32 v[14:15], v[14:15], v[18:19] op_sel_hi:[1,0]
	v_max_f32_e32 v12, 0, v12
	v_mul_f32_e32 v19, v8, v8
	v_max_f32_e32 v8, 0, v13
	v_max_f32_e32 v9, 0, v9
	v_max_f32_e32 v10, 0, v10
	v_mul_f32_e32 v12, v12, v12
	v_mul_f32_e32 v8, v8, v8
	v_mul_f32_e32 v13, v9, v9
	v_max_f32_e32 v9, 0, v14
	v_mul_f32_e32 v14, v10, v10
	v_max_f32_e32 v10, 0, v15
	v_mul_f32_e32 v9, v9, v9
	v_max_f32_e32 v11, 0, v11
	v_pk_mul_f32 v[10:11], v[10:11], v[10:11]
	v_cvt_pk_bf16_f32 v8, v12, v8
	v_add_co_u32_e32 v12, vcc, s58, v144
	v_pk_mul_f32 v[2:3], v[2:3], v[18:19] op_sel_hi:[1,0]
	v_pk_mul_f32 v[0:1], v[0:1], v[18:19] op_sel_hi:[1,0]
	v_cvt_pk_bf16_f32 v9, v9, v10
	v_cvt_pk_bf16_f32 v10, v19, v13
	v_addc_co_u32_e32 v13, vcc, 0, v145, vcc
	v_pk_mul_f32 v[6:7], v[6:7], v[18:19] op_sel_hi:[1,0]
	v_pk_mul_f32 v[4:5], v[4:5], v[18:19] op_sel_hi:[1,0]
	v_max_f32_e32 v0, 0, v0
	v_max_f32_e32 v1, 0, v1
	v_max_f32_e32 v2, 0, v2
	v_cvt_pk_bf16_f32 v11, v14, v11
	global_store_dwordx4 v[12:13], v[8:11], off nt
	v_max_f32_e32 v3, 0, v3
	v_lshl_add_u64 v[16:17], v[144:145], 0, s[18:19]
	v_mul_f32_e32 v8, v0, v0
	v_max_f32_e32 v0, 0, v5
	v_mul_f32_e32 v5, v1, v1
	v_max_f32_e32 v1, 0, v6
	v_mul_f32_e32 v6, v2, v2
	v_max_f32_e32 v2, 0, v7
	v_max_f32_e32 v4, 0, v4
	v_pk_mul_f32 v[0:1], v[0:1], v[0:1]
	v_pk_mul_f32 v[2:3], v[2:3], v[2:3]
	s_and_b64 vcc, exec, s[2:3]
	v_mul_f32_e32 v4, v4, v4
	v_cvt_pk_bf16_f32 v0, v4, v0
	v_cvt_pk_bf16_f32 v1, v1, v2
	v_cvt_pk_bf16_f32 v2, v8, v5
	v_cvt_pk_bf16_f32 v3, v6, v3
	global_store_dwordx4 v[16:17], v[0:3], off offset:256 nt
	s_cbranch_vccz .LBB0_1211
	s_waitcnt vmcnt(0)
	s_cmpk_gt_u32 s33, 0xff
	s_cbranch_scc1 .LBB0_1222
	s_barrier
